# GEMM K-loops: extra s_setprio 0/1 flip pair after every 8 MFMAs inside each MFMA segment (flips after 8,16,24 instead of only 16); on top of v23
# speedup vs baseline: 1.0011x; 1.0011x over previous
; #define PG8_STAGE(bufoff, gbase, voff) do { _Pragma("unroll") for (int _i = 0; _i < 2; ++_i) \
;         __builtin_amdgcn_global_load_lds((const unsigned*)((const char*)(gbase) + (voff)[_i]), (PG8_LAS unsigned*)(lds + (bufoff) + ldsw + _i * 8192), 16, 0, 0); } while (0)
; #define PG8_LDA(dst, b, h) do { _Pragma("unroll") for (int m = 0; m < 4; ++m) _Pragma("unroll") for (int k = 0; k < 2; ++k) dst[m][k] = *(const PG8_LAS bf16x8*)(lds + PG8_SA(b, h) + aoff + m * 2048 + k * 1024); } while (0)
; #define PG8_LDB(dst, b, h) do { _Pragma("unroll") for (int n = 0; n < 2; ++n) _Pragma("unroll") for (int k = 0; k < 2; ++k) dst[n][k] = *(const PG8_LAS bf16x8*)(lds + PG8_SB(b, h) + boff + n * 2048 + k * 1024); } while (0)
; #define PG8_MMA(ai, bj, At, Bt) do { __builtin_amdgcn_s_setprio(1); _Pragma("unroll") for (int m = 0; m < 4; ++m) _Pragma("unroll") for (int n = 0; n < 2; ++n) _Pragma("unroll") for (int k = 0; k < 2; ++k) \
;         acc[ai][bj][m][n] = __builtin_amdgcn_mfma_f32_16x16x32_bf16(Bt[n][k], At[m][k], acc[ai][bj][m][n], 0, 0, 0); __builtin_amdgcn_s_setprio(0); } while (0)
; #define PG8_WAIT_V(n) asm volatile("s_waitcnt vmcnt(" #n ")" ::: "memory")
; #define PG8_WAIT_L(n) asm volatile("s_waitcnt lgkmcnt(" #n ")" ::: "memory")
; #define PG8_BAR __builtin_amdgcn_s_barrier()
; #define PG8_SCHED __builtin_amdgcn_sched_barrier(0)
; template <class Epi, class Sched, bool ALIGN_EPI = false, bool SP2 = false>
; __device__ __forceinline__ void gemm_phase(PG8_LAS unsigned char* lds, const Gemm g, const Sched& S, const Epi& E, int wid_in) {
;     ...
;             const char* a1 = cA + (size_t)(t + 1) * kstep;
;             const char* a2 = last ? nA : cA + (size_t)(t + 2) * kstep; const char* b2 = last ? nB : cB + (size_t)(t + 2) * kstep;
;             const char* a3 = a2 + kstep; const char* b3 = b2 + kstep;
;             if (last && has_next) S.a_ready(nxt);
;             if constexpr (SP2) {
;             PG8_LDB(B0, 0, 0); PG8_LDB(B1, 0, 1); PG8_SCHED; PG8_LDA(At, 0, 0); PG8_STAGE(PG8_SA(1, 1), a1 + hstep, voffA);
;             PG8_WAIT_V(8); PG8_WAIT_L(0); PG8_BAR; PG8_MMA(0, 0, At, B0); PG8_MMA(0, 1, At, B1); PG8_BAR; PG8_SCHED;
;             PG8_LDA(At, 0, 1); PG8_STAGE(PG8_SB(0, 0), b2, voffB); PG8_STAGE(PG8_SB(0, 1), b2 + hstep, voffB); PG8_STAGE(PG8_SA(0, 0), a2, voffA);
.LBB0_227:
	ds_read_b128 v[128:131], v171
	ds_read_b128 v[132:135], v171 offset:1024
	ds_read_b128 v[158:161], v171 offset:2048
	ds_read_b128 v[162:165], v171 offset:3072
	ds_read_b128 v[174:177], v172
	ds_read_b128 v[178:181], v172 offset:1024
	ds_read_b128 v[182:185], v172 offset:2048
	ds_read_b128 v[186:189], v172 offset:3072
	s_add_u32 s88, s68, 0xfffc0080
	s_addc_u32 s89, s69, -1
	s_cmp_eq_u32 s94, 12
	s_cselect_b32 s91, s3, s89
	s_cselect_b32 s90, s5, s88
	s_cselect_b32 s89, s81, s93
	s_cselect_b32 s88, s83, s92
	v_lshl_add_u64 v[166:167], s[68:69], 0, v[150:151]
	s_add_i32 m0, s34, 0xc000
	ds_read_b128 v[190:193], v173
	ds_read_b128 v[194:197], v173 offset:1024
	ds_read_b128 v[198:201], v173 offset:2048
	ds_read_b128 v[202:205], v173 offset:3072
	ds_read_b128 v[206:209], v173 offset:4096
	ds_read_b128 v[210:213], v173 offset:5120
	ds_read_b128 v[214:217], v173 offset:6144
	ds_read_b128 v[218:221], v173 offset:7168
	global_load_lds_dwordx4 v[166:167], off
	v_lshl_add_u64 v[166:167], s[68:69], 0, v[152:153]
	s_add_i32 m0, s34, 0xe000
	s_nop 0
	global_load_lds_dwordx4 v[166:167], off
	s_waitcnt vmcnt(8)
	s_waitcnt lgkmcnt(0)
	s_barrier
	s_setprio 1
	s_waitcnt lgkmcnt(0)
	v_mfma_f32_16x16x32_bf16 v[124:127], v[128:131], v[190:193], v[124:127]
	v_mfma_f32_16x16x32_bf16 v[120:123], v[158:161], v[190:193], v[120:123]
	v_mfma_f32_16x16x32_bf16 v[108:111], v[128:131], v[198:201], v[108:111]
	v_mfma_f32_16x16x32_bf16 v[104:107], v[158:161], v[198:201], v[104:107]
	v_mfma_f32_16x16x32_bf16 v[92:95], v[128:131], v[206:209], v[92:95]
	v_mfma_f32_16x16x32_bf16 v[88:91], v[158:161], v[206:209], v[88:91]
	v_mfma_f32_16x16x32_bf16 v[76:79], v[128:131], v[214:217], v[76:79]
	v_mfma_f32_16x16x32_bf16 v[72:75], v[158:161], v[214:217], v[72:75]
	s_setprio 0
	s_setprio 1
	v_mfma_f32_16x16x32_bf16 v[124:127], v[132:135], v[194:197], v[124:127]
	v_mfma_f32_16x16x32_bf16 v[120:123], v[162:165], v[194:197], v[120:123]
	v_mfma_f32_16x16x32_bf16 v[108:111], v[132:135], v[202:205], v[108:111]
	v_mfma_f32_16x16x32_bf16 v[104:107], v[162:165], v[202:205], v[104:107]
	v_mfma_f32_16x16x32_bf16 v[92:95], v[132:135], v[210:213], v[92:95]
	v_mfma_f32_16x16x32_bf16 v[88:91], v[162:165], v[210:213], v[88:91]
	v_mfma_f32_16x16x32_bf16 v[76:79], v[132:135], v[218:221], v[76:79]
	v_mfma_f32_16x16x32_bf16 v[72:75], v[162:165], v[218:221], v[72:75]
	s_setprio 0
	s_setprio 1
	v_mfma_f32_16x16x32_bf16 v[116:119], v[174:177], v[190:193], v[116:119]
	v_mfma_f32_16x16x32_bf16 v[112:115], v[182:185], v[190:193], v[112:115]
	v_mfma_f32_16x16x32_bf16 v[100:103], v[174:177], v[198:201], v[100:103]
	v_mfma_f32_16x16x32_bf16 v[96:99], v[182:185], v[198:201], v[96:99]
	v_mfma_f32_16x16x32_bf16 v[84:87], v[174:177], v[206:209], v[84:87]
	v_mfma_f32_16x16x32_bf16 v[80:83], v[182:185], v[206:209], v[80:83]
	v_mfma_f32_16x16x32_bf16 v[68:71], v[174:177], v[214:217], v[68:71]
	v_mfma_f32_16x16x32_bf16 v[64:67], v[182:185], v[214:217], v[64:67]
	s_setprio 0
	s_setprio 1
	v_mfma_f32_16x16x32_bf16 v[116:119], v[178:181], v[194:197], v[116:119]
	v_mfma_f32_16x16x32_bf16 v[112:115], v[186:189], v[194:197], v[112:115]
	v_mfma_f32_16x16x32_bf16 v[100:103], v[178:181], v[202:205], v[100:103]
	v_mfma_f32_16x16x32_bf16 v[96:99], v[186:189], v[202:205], v[96:99]
	v_mfma_f32_16x16x32_bf16 v[84:87], v[178:181], v[210:213], v[84:87]
	v_mfma_f32_16x16x32_bf16 v[80:83], v[186:189], v[210:213], v[80:83]
	v_mfma_f32_16x16x32_bf16 v[68:71], v[178:181], v[218:221], v[68:71]
	v_mfma_f32_16x16x32_bf16 v[64:67], v[186:189], v[218:221], v[64:67]
	s_setprio 0
	s_barrier
	s_add_i32 s95, s70, s12
	v_lshl_add_u64 v[166:167], s[88:89], 0, v[138:139]
	s_mov_b32 m0, s95
	ds_read_b128 v[190:193], v173 offset:16384
	ds_read_b128 v[194:197], v173 offset:17408
	ds_read_b128 v[198:201], v173 offset:18432
	ds_read_b128 v[202:205], v173 offset:19456
	ds_read_b128 v[206:209], v173 offset:20480
	ds_read_b128 v[210:213], v173 offset:21504
	ds_read_b128 v[214:217], v173 offset:22528
	ds_read_b128 v[218:221], v173 offset:23552
	global_load_lds_dwordx4 v[166:167], off
	s_add_i32 m0, s95, 0x2000
	s_add_u32 vcc_lo, s88, 0x40000
	v_lshl_add_u64 v[222:223], s[88:89], 0, v[142:143]
	s_addc_u32 vcc_hi, s89, 0
	s_add_i32 s95, s71, s12
	global_load_lds_dwordx4 v[222:223], off
	v_lshl_add_u64 v[224:225], vcc, 0, v[138:139]
	s_mov_b32 m0, s95
	v_lshl_add_u64 v[226:227], s[90:91], 0, v[140:141]
	global_load_lds_dwordx4 v[224:225], off
	v_lshl_add_u64 v[224:225], vcc, 0, v[142:143]
	s_add_i32 m0, s95, 0x2000
	s_nop 0
	global_load_lds_dwordx4 v[224:225], off
	v_lshl_add_u64 v[224:225], s[90:91], 0, v[136:137]
	s_mov_b32 m0, s34
	s_nop 0
	global_load_lds_dwordx4 v[224:225], off
	s_mov_b32 m0, s35
	s_nop 0
	global_load_lds_dwordx4 v[226:227], off
	s_waitcnt vmcnt(8)
	s_waitcnt lgkmcnt(0)
	s_barrier
; #define PG8_STAGE(bufoff, gbase, voff) do { _Pragma("unroll") for (int _i = 0; _i < 2; ++_i) \
;         __builtin_amdgcn_global_load_lds((const unsigned*)((const char*)(gbase) + (voff)[_i]), (PG8_LAS unsigned*)(lds + (bufoff) + ldsw + _i * 8192), 16, 0, 0); } while (0)
; #define PG8_LDA(dst, b, h) do { _Pragma("unroll") for (int m = 0; m < 4; ++m) _Pragma("unroll") for (int k = 0; k < 2; ++k) dst[m][k] = *(const PG8_LAS bf16x8*)(lds + PG8_SA(b, h) + aoff + m * 2048 + k * 1024); } while (0)
; #define PG8_LDB(dst, b, h) do { _Pragma("unroll") for (int n = 0; n < 2; ++n) _Pragma("unroll") for (int k = 0; k < 2; ++k) dst[n][k] = *(const PG8_LAS bf16x8*)(lds + PG8_SB(b, h) + boff + n * 2048 + k * 1024); } while (0)
; #define PG8_MMA(ai, bj, At, Bt) do { __builtin_amdgcn_s_setprio(1); _Pragma("unroll") for (int m = 0; m < 4; ++m) _Pragma("unroll") for (int n = 0; n < 2; ++n) _Pragma("unroll") for (int k = 0; k < 2; ++k) \
;         acc[ai][bj][m][n] = __builtin_amdgcn_mfma_f32_16x16x32_bf16(Bt[n][k], At[m][k], acc[ai][bj][m][n], 0, 0, 0); __builtin_amdgcn_s_setprio(0); } while (0)
; #define PG8_WAIT_V(n) asm volatile("s_waitcnt vmcnt(" #n ")" ::: "memory")
; #define PG8_WAIT_L(n) asm volatile("s_waitcnt lgkmcnt(" #n ")" ::: "memory")
; #define PG8_BAR __builtin_amdgcn_s_barrier()
; #define PG8_SCHED __builtin_amdgcn_sched_barrier(0)
; template <class Epi, class Sched, bool ALIGN_EPI = false, bool SP2 = false>
; __device__ __forceinline__ void gemm_phase(PG8_LAS unsigned char* lds, const Gemm g, const Sched& S, const Epi& E, int wid_in) {
;     ...
;             PG8_WAIT_V(8); PG8_WAIT_L(0); PG8_BAR; PG8_MMA(1, 0, At, B0); PG8_MMA(1, 1, At, B1); PG8_BAR; PG8_SCHED;
;             PG8_LDB(B0, 1, 0); PG8_LDB(B1, 1, 1); PG8_SCHED; PG8_LDA(At, 1, 0); PG8_STAGE(PG8_SA(0, 1), a2 + hstep, voffA);
;             PG8_WAIT_V(8); PG8_WAIT_L(0); PG8_BAR; PG8_MMA(0, 0, At, B0); PG8_MMA(0, 1, At, B1); PG8_BAR; PG8_SCHED;
;             PG8_LDA(At, 1, 1); PG8_STAGE(PG8_SB(1, 0), b3, voffB); PG8_STAGE(PG8_SB(1, 1), b3 + hstep, voffB); PG8_STAGE(PG8_SA(1, 0), a3, voffA);
	s_setprio 1
	s_waitcnt lgkmcnt(0)
	v_mfma_f32_16x16x32_bf16 v[60:63], v[128:131], v[190:193], v[60:63]
	v_mfma_f32_16x16x32_bf16 v[56:59], v[158:161], v[190:193], v[56:59]
	v_mfma_f32_16x16x32_bf16 v[44:47], v[128:131], v[198:201], v[44:47]
	v_mfma_f32_16x16x32_bf16 v[40:43], v[158:161], v[198:201], v[40:43]
	v_mfma_f32_16x16x32_bf16 v[28:31], v[128:131], v[206:209], v[28:31]
	v_mfma_f32_16x16x32_bf16 v[24:27], v[158:161], v[206:209], v[24:27]
	v_mfma_f32_16x16x32_bf16 v[12:15], v[128:131], v[214:217], v[12:15]
	v_mfma_f32_16x16x32_bf16 v[8:11], v[158:161], v[214:217], v[8:11]
	s_setprio 0
	s_setprio 1
	v_mfma_f32_16x16x32_bf16 v[60:63], v[132:135], v[194:197], v[60:63]
	v_mfma_f32_16x16x32_bf16 v[56:59], v[162:165], v[194:197], v[56:59]
	v_mfma_f32_16x16x32_bf16 v[44:47], v[132:135], v[202:205], v[44:47]
	v_mfma_f32_16x16x32_bf16 v[40:43], v[162:165], v[202:205], v[40:43]
	v_mfma_f32_16x16x32_bf16 v[28:31], v[132:135], v[210:213], v[28:31]
	v_mfma_f32_16x16x32_bf16 v[24:27], v[162:165], v[210:213], v[24:27]
	v_mfma_f32_16x16x32_bf16 v[12:15], v[132:135], v[218:221], v[12:15]
	v_mfma_f32_16x16x32_bf16 v[8:11], v[162:165], v[218:221], v[8:11]
	s_setprio 0
	s_setprio 1
	v_mfma_f32_16x16x32_bf16 v[52:55], v[174:177], v[190:193], v[52:55]
	v_mfma_f32_16x16x32_bf16 v[48:51], v[182:185], v[190:193], v[48:51]
	v_mfma_f32_16x16x32_bf16 v[36:39], v[174:177], v[198:201], v[36:39]
	v_mfma_f32_16x16x32_bf16 v[32:35], v[182:185], v[198:201], v[32:35]
	v_mfma_f32_16x16x32_bf16 v[20:23], v[174:177], v[206:209], v[20:23]
	v_mfma_f32_16x16x32_bf16 v[16:19], v[182:185], v[206:209], v[16:19]
	v_mfma_f32_16x16x32_bf16 v[4:7], v[174:177], v[214:217], v[4:7]
	v_mfma_f32_16x16x32_bf16 v[0:3], v[182:185], v[214:217], v[0:3]
	s_setprio 0
	s_setprio 1
	v_mfma_f32_16x16x32_bf16 v[52:55], v[178:181], v[194:197], v[52:55]
	v_mfma_f32_16x16x32_bf16 v[48:51], v[186:189], v[194:197], v[48:51]
	v_mfma_f32_16x16x32_bf16 v[36:39], v[178:181], v[202:205], v[36:39]
	v_mfma_f32_16x16x32_bf16 v[32:35], v[186:189], v[202:205], v[32:35]
	v_mfma_f32_16x16x32_bf16 v[20:23], v[178:181], v[210:213], v[20:23]
	v_mfma_f32_16x16x32_bf16 v[16:19], v[186:189], v[210:213], v[16:19]
	v_mfma_f32_16x16x32_bf16 v[4:7], v[178:181], v[218:221], v[4:7]
	v_mfma_f32_16x16x32_bf16 v[0:3], v[186:189], v[218:221], v[0:3]
	s_setprio 0
	s_barrier
	s_add_i32 s95, 0, 0x18000
	v_add_u32_e32 v144, s95, v169
	s_add_i32 vcc_lo, 0, 0x1c000
	ds_read_b128 v[128:131], v144
	ds_read_b128 v[132:135], v144 offset:1024
	ds_read_b128 v[158:161], v144 offset:2048
	ds_read_b128 v[162:165], v144 offset:3072
	v_add_u32_e32 v144, vcc_lo, v169
	ds_read_b128 v[174:177], v144
	ds_read_b128 v[178:181], v144 offset:1024
	ds_read_b128 v[182:185], v144 offset:2048
	ds_read_b128 v[186:189], v144 offset:3072
	s_add_u32 s90, s90, 0x40000
	s_addc_u32 s91, s91, 0
	s_mov_b32 m0, s61
	v_lshl_add_u64 v[228:229], s[90:91], 0, v[136:137]
	ds_read_b128 v[190:193], v173 offset:32768
	ds_read_b128 v[194:197], v173 offset:33792
	ds_read_b128 v[198:201], v173 offset:34816
	ds_read_b128 v[202:205], v173 offset:35840
	ds_read_b128 v[206:209], v173 offset:36864
	ds_read_b128 v[210:213], v173 offset:37888
	ds_read_b128 v[214:217], v173 offset:38912
	ds_read_b128 v[218:221], v173 offset:39936
	global_load_lds_dwordx4 v[228:229], off
	v_lshl_add_u64 v[228:229], s[90:91], 0, v[140:141]
	s_mov_b32 m0, s62
	s_nop 0
	global_load_lds_dwordx4 v[228:229], off
	s_waitcnt vmcnt(8)
	s_waitcnt lgkmcnt(0)
	s_barrier
	s_setprio 1
	s_waitcnt lgkmcnt(0)
	v_mfma_f32_16x16x32_bf16 v[124:127], v[128:131], v[190:193], v[124:127]
	v_mfma_f32_16x16x32_bf16 v[120:123], v[158:161], v[190:193], v[120:123]
	v_mfma_f32_16x16x32_bf16 v[108:111], v[128:131], v[198:201], v[108:111]
	v_mfma_f32_16x16x32_bf16 v[104:107], v[158:161], v[198:201], v[104:107]
	v_mfma_f32_16x16x32_bf16 v[92:95], v[128:131], v[206:209], v[92:95]
	v_mfma_f32_16x16x32_bf16 v[88:91], v[158:161], v[206:209], v[88:91]
	v_mfma_f32_16x16x32_bf16 v[76:79], v[128:131], v[214:217], v[76:79]
	v_mfma_f32_16x16x32_bf16 v[72:75], v[158:161], v[214:217], v[72:75]
	s_setprio 0
	s_setprio 1
	v_mfma_f32_16x16x32_bf16 v[124:127], v[132:135], v[194:197], v[124:127]
	v_mfma_f32_16x16x32_bf16 v[120:123], v[162:165], v[194:197], v[120:123]
	v_mfma_f32_16x16x32_bf16 v[108:111], v[132:135], v[202:205], v[108:111]
	v_mfma_f32_16x16x32_bf16 v[104:107], v[162:165], v[202:205], v[104:107]
	v_mfma_f32_16x16x32_bf16 v[92:95], v[132:135], v[210:213], v[92:95]
	v_mfma_f32_16x16x32_bf16 v[88:91], v[162:165], v[210:213], v[88:91]
	v_mfma_f32_16x16x32_bf16 v[76:79], v[132:135], v[218:221], v[76:79]
	v_mfma_f32_16x16x32_bf16 v[72:75], v[162:165], v[218:221], v[72:75]
	s_setprio 0
	s_setprio 1
	v_mfma_f32_16x16x32_bf16 v[116:119], v[174:177], v[190:193], v[116:119]
	v_mfma_f32_16x16x32_bf16 v[112:115], v[182:185], v[190:193], v[112:115]
	v_mfma_f32_16x16x32_bf16 v[100:103], v[174:177], v[198:201], v[100:103]
	v_mfma_f32_16x16x32_bf16 v[96:99], v[182:185], v[198:201], v[96:99]
	v_mfma_f32_16x16x32_bf16 v[84:87], v[174:177], v[206:209], v[84:87]
	v_mfma_f32_16x16x32_bf16 v[80:83], v[182:185], v[206:209], v[80:83]
	v_mfma_f32_16x16x32_bf16 v[68:71], v[174:177], v[214:217], v[68:71]
	v_mfma_f32_16x16x32_bf16 v[64:67], v[182:185], v[214:217], v[64:67]
	s_setprio 0
	s_setprio 1
	v_mfma_f32_16x16x32_bf16 v[116:119], v[178:181], v[194:197], v[116:119]
	v_mfma_f32_16x16x32_bf16 v[112:115], v[186:189], v[194:197], v[112:115]
	v_mfma_f32_16x16x32_bf16 v[100:103], v[178:181], v[202:205], v[100:103]
	v_mfma_f32_16x16x32_bf16 v[96:99], v[186:189], v[202:205], v[96:99]
	v_mfma_f32_16x16x32_bf16 v[84:87], v[178:181], v[210:213], v[84:87]
	v_mfma_f32_16x16x32_bf16 v[80:83], v[186:189], v[210:213], v[80:83]
	v_mfma_f32_16x16x32_bf16 v[68:71], v[178:181], v[218:221], v[68:71]
	v_mfma_f32_16x16x32_bf16 v[64:67], v[186:189], v[218:221], v[64:67]
	s_setprio 0
	s_barrier
; #define PG8_STAGE(bufoff, gbase, voff) do { _Pragma("unroll") for (int _i = 0; _i < 2; ++_i) \
;         __builtin_amdgcn_global_load_lds((const unsigned*)((const char*)(gbase) + (voff)[_i]), (PG8_LAS unsigned*)(lds + (bufoff) + ldsw + _i * 8192), 16, 0, 0); } while (0)
; #define PG8_LDA(dst, b, h) do { _Pragma("unroll") for (int m = 0; m < 4; ++m) _Pragma("unroll") for (int k = 0; k < 2; ++k) dst[m][k] = *(const PG8_LAS bf16x8*)(lds + PG8_SA(b, h) + aoff + m * 2048 + k * 1024); } while (0)
; #define PG8_MMA(ai, bj, At, Bt) do { __builtin_amdgcn_s_setprio(1); _Pragma("unroll") for (int m = 0; m < 4; ++m) _Pragma("unroll") for (int n = 0; n < 2; ++n) _Pragma("unroll") for (int k = 0; k < 2; ++k) \
;         acc[ai][bj][m][n] = __builtin_amdgcn_mfma_f32_16x16x32_bf16(Bt[n][k], At[m][k], acc[ai][bj][m][n], 0, 0, 0); __builtin_amdgcn_s_setprio(0); } while (0)
; #define PG8_WAIT_V(n) asm volatile("s_waitcnt vmcnt(" #n ")" ::: "memory")
; #define PG8_WAIT_L(n) asm volatile("s_waitcnt lgkmcnt(" #n ")" ::: "memory")
; #define PG8_BAR __builtin_amdgcn_s_barrier()
; #define PG8_SCHED __builtin_amdgcn_sched_barrier(0)
; template <class Epi, class Sched, bool ALIGN_EPI = false, bool SP2 = false>
; __device__ __forceinline__ void gemm_phase(PG8_LAS unsigned char* lds, const Gemm g, const Sched& S, const Epi& E, int wid_in) {
;     ...
;             PG8_LDA(At, 1, 1); PG8_STAGE(PG8_SB(1, 0), b3, voffB); PG8_STAGE(PG8_SB(1, 1), b3 + hstep, voffB); PG8_STAGE(PG8_SA(1, 0), a3, voffA);
;             PG8_WAIT_V(8); PG8_WAIT_L(0); PG8_BAR; PG8_MMA(1, 0, At, B0); PG8_MMA(1, 1, At, B1); PG8_BAR; PG8_SCHED;
;     ...
;         if constexpr (ALIGN_EPI) { if (wr == 0) PG8_BAR; }
	s_add_i32 s90, s95, s12
	v_lshl_add_u64 v[166:167], v[166:167], 0, s[74:75]
	s_mov_b32 m0, s90
	ds_read_b128 v[190:193], v173 offset:49152
	ds_read_b128 v[194:197], v173 offset:50176
	ds_read_b128 v[198:201], v173 offset:51200
	ds_read_b128 v[202:205], v173 offset:52224
	ds_read_b128 v[206:209], v173 offset:53248
	ds_read_b128 v[210:213], v173 offset:54272
	ds_read_b128 v[214:217], v173 offset:55296
	ds_read_b128 v[218:221], v173 offset:56320
	global_load_lds_dwordx4 v[166:167], off
	s_add_i32 m0, s90, 0x2000
	s_add_u32 s88, s88, 0x40080
	v_lshl_add_u64 v[166:167], v[222:223], 0, s[74:75]
	s_addc_u32 s89, s89, 0
	s_add_i32 s90, vcc_lo, s12
	global_load_lds_dwordx4 v[166:167], off
	v_lshl_add_u64 v[166:167], s[88:89], 0, v[138:139]
	s_mov_b32 m0, s90
	s_nop 0
	global_load_lds_dwordx4 v[166:167], off
	v_lshl_add_u64 v[166:167], s[88:89], 0, v[142:143]
	s_add_i32 m0, s90, 0x2000
	s_nop 0
	global_load_lds_dwordx4 v[166:167], off
	v_lshl_add_u64 v[166:167], v[224:225], 0, s[74:75]
	s_mov_b32 m0, s64
	s_nop 0
	global_load_lds_dwordx4 v[166:167], off
	v_lshl_add_u64 v[166:167], v[226:227], 0, s[74:75]
	s_mov_b32 m0, s65
	s_nop 0
	global_load_lds_dwordx4 v[166:167], off
	s_waitcnt vmcnt(8)
	s_waitcnt lgkmcnt(0)
	s_barrier
	s_setprio 1
	s_waitcnt lgkmcnt(0)
	v_mfma_f32_16x16x32_bf16 v[60:63], v[128:131], v[190:193], v[60:63]
	v_mfma_f32_16x16x32_bf16 v[56:59], v[158:161], v[190:193], v[56:59]
	v_mfma_f32_16x16x32_bf16 v[44:47], v[128:131], v[198:201], v[44:47]
	v_mfma_f32_16x16x32_bf16 v[40:43], v[158:161], v[198:201], v[40:43]
	v_mfma_f32_16x16x32_bf16 v[28:31], v[128:131], v[206:209], v[28:31]
	v_mfma_f32_16x16x32_bf16 v[24:27], v[158:161], v[206:209], v[24:27]
	v_mfma_f32_16x16x32_bf16 v[12:15], v[128:131], v[214:217], v[12:15]
	v_mfma_f32_16x16x32_bf16 v[8:11], v[158:161], v[214:217], v[8:11]
	s_setprio 0
	s_setprio 1
	v_mfma_f32_16x16x32_bf16 v[60:63], v[132:135], v[194:197], v[60:63]
	v_mfma_f32_16x16x32_bf16 v[56:59], v[162:165], v[194:197], v[56:59]
	v_mfma_f32_16x16x32_bf16 v[44:47], v[132:135], v[202:205], v[44:47]
	v_mfma_f32_16x16x32_bf16 v[40:43], v[162:165], v[202:205], v[40:43]
	v_mfma_f32_16x16x32_bf16 v[28:31], v[132:135], v[210:213], v[28:31]
	v_mfma_f32_16x16x32_bf16 v[24:27], v[162:165], v[210:213], v[24:27]
	v_mfma_f32_16x16x32_bf16 v[12:15], v[132:135], v[218:221], v[12:15]
	v_mfma_f32_16x16x32_bf16 v[8:11], v[162:165], v[218:221], v[8:11]
	s_setprio 0
	s_setprio 1
	v_mfma_f32_16x16x32_bf16 v[52:55], v[174:177], v[190:193], v[52:55]
	v_mfma_f32_16x16x32_bf16 v[48:51], v[182:185], v[190:193], v[48:51]
	v_mfma_f32_16x16x32_bf16 v[36:39], v[174:177], v[198:201], v[36:39]
	v_mfma_f32_16x16x32_bf16 v[32:35], v[182:185], v[198:201], v[32:35]
	v_mfma_f32_16x16x32_bf16 v[20:23], v[174:177], v[206:209], v[20:23]
	v_mfma_f32_16x16x32_bf16 v[16:19], v[182:185], v[206:209], v[16:19]
	v_mfma_f32_16x16x32_bf16 v[4:7], v[174:177], v[214:217], v[4:7]
	v_mfma_f32_16x16x32_bf16 v[0:3], v[182:185], v[214:217], v[0:3]
	s_setprio 0
	s_setprio 1
	v_mfma_f32_16x16x32_bf16 v[52:55], v[178:181], v[194:197], v[52:55]
	v_mfma_f32_16x16x32_bf16 v[48:51], v[186:189], v[194:197], v[48:51]
	v_mfma_f32_16x16x32_bf16 v[36:39], v[178:181], v[202:205], v[36:39]
	v_mfma_f32_16x16x32_bf16 v[32:35], v[186:189], v[202:205], v[32:35]
	v_mfma_f32_16x16x32_bf16 v[20:23], v[178:181], v[210:213], v[20:23]
	v_mfma_f32_16x16x32_bf16 v[16:19], v[186:189], v[210:213], v[16:19]
	v_mfma_f32_16x16x32_bf16 v[4:7], v[178:181], v[218:221], v[4:7]
	v_mfma_f32_16x16x32_bf16 v[0:3], v[186:189], v[218:221], v[0:3]
	s_setprio 0
	s_barrier
	s_add_i32 s94, s94, 2
	s_add_u32 s68, s68, 0x100
	s_addc_u32 s69, s69, 0
	s_add_u32 s92, s92, 0x100
	s_addc_u32 s93, s93, 0
	s_cmp_gt_u32 s94, 13
	s_cbranch_scc0 .LBB0_227
	s_and_b64 vcc, exec, s[76:77]
	s_cbranch_vccz .LBB0_230
	s_barrier

; template <int ROT, class Epi0, class Epi1, class Late, class Post0>
; __device__ __forceinline__ void gemm_phase_pair(PG8_LAS unsigned char* lds, const Gemm g0, const Gemm g1, const Unit u, const Epi0& E0, const Epi1& E1, int wid_in, const Late& late, const Post0& post0) {
;     ...
;     for (int t = 0; t < t_late; t += 2) {
;         const char* a1 = cA + PG8_KT(t + 1); const char* a2 = cA + PG8_KT(t + 2); const char* b2 = cB + PG8_KT(t + 2); const char* a3 = cA + PG8_KT(t + 3); const char* b3 = cB + PG8_KT(t + 3);
;         PG8_PAIR_ITER(a1 + hs0, vA0, a2, b2, a3, b3, vA0, vB0, hs0);
.LBB0_847:
	s_nop 0
	ds_read_b128 v[144:147], v141
	ds_read_b128 v[148:151], v141 offset:1024
	ds_read_b128 v[152:155], v141 offset:2048
	ds_read_b128 v[156:159], v141 offset:3072
	ds_read_b128 v[160:163], v140
	ds_read_b128 v[164:167], v140 offset:1024
	ds_read_b128 v[168:171], v140 offset:2048
	ds_read_b128 v[172:175], v140 offset:3072
	s_add_u32 s62, s38, s18
	s_addc_u32 s63, s39, s19
	v_lshl_add_u64 v[208:209], s[62:63], 0, v[130:131]
	s_mov_b32 m0, s51
	v_lshl_add_u64 v[210:211], v[208:209], 0, s[4:5]
	v_mov_b32_e32 v129, v131
	ds_read_b128 v[176:179], v137
	ds_read_b128 v[180:183], v137 offset:1024
	ds_read_b128 v[184:187], v137 offset:2048
	ds_read_b128 v[188:191], v137 offset:3072
	ds_read_b128 v[192:195], v137 offset:4096
	ds_read_b128 v[196:199], v137 offset:5120
	ds_read_b128 v[200:203], v137 offset:6144
	ds_read_b128 v[204:207], v137 offset:7168
	global_load_lds_dwordx4 v[210:211], off
	v_lshl_add_u64 v[210:211], s[62:63], 0, v[128:129]
	v_lshl_add_u64 v[212:213], v[210:211], 0, s[4:5]
	s_mov_b32 m0, s50
	s_nop 0
	global_load_lds_dwordx4 v[212:213], off
	s_waitcnt vmcnt(8)
	s_waitcnt lgkmcnt(0)
	s_barrier
	s_setprio 1
	s_waitcnt lgkmcnt(0)
	v_mfma_f32_16x16x32_bf16 v[124:127], v[144:147], v[176:179], v[124:127]
	v_mfma_f32_16x16x32_bf16 v[120:123], v[152:155], v[176:179], v[120:123]
	v_mfma_f32_16x16x32_bf16 v[116:119], v[144:147], v[184:187], v[116:119]
	v_mfma_f32_16x16x32_bf16 v[112:115], v[152:155], v[184:187], v[112:115]
	v_mfma_f32_16x16x32_bf16 v[108:111], v[144:147], v[192:195], v[108:111]
	v_mfma_f32_16x16x32_bf16 v[104:107], v[152:155], v[192:195], v[104:107]
	v_mfma_f32_16x16x32_bf16 v[100:103], v[144:147], v[200:203], v[100:103]
	v_mfma_f32_16x16x32_bf16 v[96:99], v[152:155], v[200:203], v[96:99]
	s_setprio 0
	s_setprio 1
	v_mfma_f32_16x16x32_bf16 v[124:127], v[148:151], v[180:183], v[124:127]
	v_mfma_f32_16x16x32_bf16 v[120:123], v[156:159], v[180:183], v[120:123]
	v_mfma_f32_16x16x32_bf16 v[116:119], v[148:151], v[188:191], v[116:119]
	v_mfma_f32_16x16x32_bf16 v[112:115], v[156:159], v[188:191], v[112:115]
	v_mfma_f32_16x16x32_bf16 v[108:111], v[148:151], v[196:199], v[108:111]
	v_mfma_f32_16x16x32_bf16 v[104:107], v[156:159], v[196:199], v[104:107]
	v_mfma_f32_16x16x32_bf16 v[100:103], v[148:151], v[204:207], v[100:103]
	v_mfma_f32_16x16x32_bf16 v[96:99], v[156:159], v[204:207], v[96:99]
	s_setprio 0
	s_setprio 1
	v_mfma_f32_16x16x32_bf16 v[92:95], v[160:163], v[176:179], v[92:95]
	v_mfma_f32_16x16x32_bf16 v[88:91], v[168:171], v[176:179], v[88:91]
	v_mfma_f32_16x16x32_bf16 v[84:87], v[160:163], v[184:187], v[84:87]
	v_mfma_f32_16x16x32_bf16 v[80:83], v[168:171], v[184:187], v[80:83]
	v_mfma_f32_16x16x32_bf16 v[76:79], v[160:163], v[192:195], v[76:79]
	v_mfma_f32_16x16x32_bf16 v[72:75], v[168:171], v[192:195], v[72:75]
	v_mfma_f32_16x16x32_bf16 v[68:71], v[160:163], v[200:203], v[68:71]
	v_mfma_f32_16x16x32_bf16 v[64:67], v[168:171], v[200:203], v[64:67]
	s_setprio 0
	s_setprio 1
	v_mfma_f32_16x16x32_bf16 v[92:95], v[164:167], v[180:183], v[92:95]
	v_mfma_f32_16x16x32_bf16 v[88:91], v[172:175], v[180:183], v[88:91]
	v_mfma_f32_16x16x32_bf16 v[84:87], v[164:167], v[188:191], v[84:87]
	v_mfma_f32_16x16x32_bf16 v[80:83], v[172:175], v[188:191], v[80:83]
	v_mfma_f32_16x16x32_bf16 v[76:79], v[164:167], v[196:199], v[76:79]
	v_mfma_f32_16x16x32_bf16 v[72:75], v[172:175], v[196:199], v[72:75]
	v_mfma_f32_16x16x32_bf16 v[68:71], v[164:167], v[204:207], v[68:71]
	v_mfma_f32_16x16x32_bf16 v[64:67], v[172:175], v[204:207], v[64:67]
	s_setprio 0
	s_barrier
	s_add_u32 s62, s38, s20
	v_mov_b32_e32 v133, v131
	s_addc_u32 s63, s39, s21
	v_lshl_add_u64 v[212:213], s[62:63], 0, v[132:133]
	s_mov_b32 m0, s49
	v_lshl_add_u64 v[214:215], v[212:213], 0, s[6:7]
	v_mov_b32_e32 v135, v131
	ds_read_b128 v[176:179], v137 offset:16384
	ds_read_b128 v[180:183], v137 offset:17408
	ds_read_b128 v[184:187], v137 offset:18432
	ds_read_b128 v[188:191], v137 offset:19456
	ds_read_b128 v[192:195], v137 offset:20480
	ds_read_b128 v[196:199], v137 offset:21504
	ds_read_b128 v[200:203], v137 offset:22528
	ds_read_b128 v[204:207], v137 offset:23552
	global_load_lds_dwordx4 v[214:215], off
	v_lshl_add_u64 v[214:215], s[62:63], 0, v[134:135]
	v_lshl_add_u64 v[216:217], v[214:215], 0, s[6:7]
	s_mov_b32 m0, s47
	s_nop 0
	global_load_lds_dwordx4 v[216:217], off
	v_lshl_add_u64 v[216:217], v[212:213], 0, s[10:11]
	s_mov_b32 m0, s48
	s_nop 0
	global_load_lds_dwordx4 v[216:217], off
	v_lshl_add_u64 v[216:217], v[214:215], 0, s[10:11]
	s_mov_b32 m0, s46
	s_nop 0
	global_load_lds_dwordx4 v[216:217], off
	v_lshl_add_u64 v[216:217], v[208:209], 0, s[24:25]
	s_mov_b32 m0, s40
	s_nop 0
	global_load_lds_dwordx4 v[216:217], off
	v_lshl_add_u64 v[216:217], v[210:211], 0, s[24:25]
	s_mov_b32 m0, s45
	s_nop 0
	global_load_lds_dwordx4 v[216:217], off
	s_waitcnt vmcnt(8)
	s_waitcnt lgkmcnt(0)
	s_barrier
	s_setprio 1
	s_waitcnt lgkmcnt(0)
	v_mfma_f32_16x16x32_bf16 v[60:63], v[144:147], v[176:179], v[60:63]
	v_mfma_f32_16x16x32_bf16 v[56:59], v[152:155], v[176:179], v[56:59]
	v_mfma_f32_16x16x32_bf16 v[52:55], v[144:147], v[184:187], v[52:55]
	v_mfma_f32_16x16x32_bf16 v[48:51], v[152:155], v[184:187], v[48:51]
	v_mfma_f32_16x16x32_bf16 v[44:47], v[144:147], v[192:195], v[44:47]
	v_mfma_f32_16x16x32_bf16 v[40:43], v[152:155], v[192:195], v[40:43]
	v_mfma_f32_16x16x32_bf16 v[36:39], v[144:147], v[200:203], v[36:39]
	v_mfma_f32_16x16x32_bf16 v[32:35], v[152:155], v[200:203], v[32:35]
	s_setprio 0
	s_setprio 1
	v_mfma_f32_16x16x32_bf16 v[60:63], v[148:151], v[180:183], v[60:63]
	v_mfma_f32_16x16x32_bf16 v[56:59], v[156:159], v[180:183], v[56:59]
	v_mfma_f32_16x16x32_bf16 v[52:55], v[148:151], v[188:191], v[52:55]
	v_mfma_f32_16x16x32_bf16 v[48:51], v[156:159], v[188:191], v[48:51]
	v_mfma_f32_16x16x32_bf16 v[44:47], v[148:151], v[196:199], v[44:47]
	v_mfma_f32_16x16x32_bf16 v[40:43], v[156:159], v[196:199], v[40:43]
	v_mfma_f32_16x16x32_bf16 v[36:39], v[148:151], v[204:207], v[36:39]
	v_mfma_f32_16x16x32_bf16 v[32:35], v[156:159], v[204:207], v[32:35]
	s_setprio 0
	s_setprio 1
	v_mfma_f32_16x16x32_bf16 v[28:31], v[160:163], v[176:179], v[28:31]
	v_mfma_f32_16x16x32_bf16 v[24:27], v[168:171], v[176:179], v[24:27]
	v_mfma_f32_16x16x32_bf16 v[20:23], v[160:163], v[184:187], v[20:23]
	v_mfma_f32_16x16x32_bf16 v[16:19], v[168:171], v[184:187], v[16:19]
	v_mfma_f32_16x16x32_bf16 v[12:15], v[160:163], v[192:195], v[12:15]
	v_mfma_f32_16x16x32_bf16 v[8:11], v[168:171], v[192:195], v[8:11]
	v_mfma_f32_16x16x32_bf16 v[4:7], v[160:163], v[200:203], v[4:7]
	v_mfma_f32_16x16x32_bf16 v[0:3], v[168:171], v[200:203], v[0:3]
	s_setprio 0
	s_setprio 1
	v_mfma_f32_16x16x32_bf16 v[28:31], v[164:167], v[180:183], v[28:31]
	v_mfma_f32_16x16x32_bf16 v[24:27], v[172:175], v[180:183], v[24:27]
	v_mfma_f32_16x16x32_bf16 v[20:23], v[164:167], v[188:191], v[20:23]
	v_mfma_f32_16x16x32_bf16 v[16:19], v[172:175], v[188:191], v[16:19]
	v_mfma_f32_16x16x32_bf16 v[12:15], v[164:167], v[196:199], v[12:15]
	v_mfma_f32_16x16x32_bf16 v[8:11], v[172:175], v[196:199], v[8:11]
	v_mfma_f32_16x16x32_bf16 v[4:7], v[164:167], v[204:207], v[4:7]
	v_mfma_f32_16x16x32_bf16 v[0:3], v[172:175], v[204:207], v[0:3]
	s_setprio 0
	s_barrier
	ds_read_b128 v[144:147], v139
	ds_read_b128 v[148:151], v139 offset:1024
	ds_read_b128 v[152:155], v139 offset:2048
	ds_read_b128 v[156:159], v139 offset:3072
	ds_read_b128 v[160:163], v138
	ds_read_b128 v[164:167], v138 offset:1024
	ds_read_b128 v[168:171], v138 offset:2048
	ds_read_b128 v[172:175], v138 offset:3072
	s_mov_b32 m0, s34
	v_lshl_add_u64 v[216:217], v[208:209], 0, s[26:27]
	ds_read_b128 v[176:179], v137 offset:32768
	ds_read_b128 v[180:183], v137 offset:33792
	ds_read_b128 v[184:187], v137 offset:34816
	ds_read_b128 v[188:191], v137 offset:35840
	ds_read_b128 v[192:195], v137 offset:36864
	ds_read_b128 v[196:199], v137 offset:37888
	ds_read_b128 v[200:203], v137 offset:38912
	ds_read_b128 v[204:207], v137 offset:39936
	global_load_lds_dwordx4 v[216:217], off
	v_lshl_add_u64 v[216:217], v[210:211], 0, s[26:27]
	s_mov_b32 m0, s35
	s_nop 0
	global_load_lds_dwordx4 v[216:217], off
	s_waitcnt vmcnt(8)
	s_waitcnt lgkmcnt(0)
	s_barrier
	s_setprio 1
	s_waitcnt lgkmcnt(0)
	v_mfma_f32_16x16x32_bf16 v[124:127], v[144:147], v[176:179], v[124:127]
	v_mfma_f32_16x16x32_bf16 v[120:123], v[152:155], v[176:179], v[120:123]
	v_mfma_f32_16x16x32_bf16 v[116:119], v[144:147], v[184:187], v[116:119]
	v_mfma_f32_16x16x32_bf16 v[112:115], v[152:155], v[184:187], v[112:115]
	v_mfma_f32_16x16x32_bf16 v[108:111], v[144:147], v[192:195], v[108:111]
	v_mfma_f32_16x16x32_bf16 v[104:107], v[152:155], v[192:195], v[104:107]
	v_mfma_f32_16x16x32_bf16 v[100:103], v[144:147], v[200:203], v[100:103]
	v_mfma_f32_16x16x32_bf16 v[96:99], v[152:155], v[200:203], v[96:99]
	s_setprio 0
	s_setprio 1
	v_mfma_f32_16x16x32_bf16 v[124:127], v[148:151], v[180:183], v[124:127]
	v_mfma_f32_16x16x32_bf16 v[120:123], v[156:159], v[180:183], v[120:123]
	v_mfma_f32_16x16x32_bf16 v[116:119], v[148:151], v[188:191], v[116:119]
	v_mfma_f32_16x16x32_bf16 v[112:115], v[156:159], v[188:191], v[112:115]
	v_mfma_f32_16x16x32_bf16 v[108:111], v[148:151], v[196:199], v[108:111]
	v_mfma_f32_16x16x32_bf16 v[104:107], v[156:159], v[196:199], v[104:107]
	v_mfma_f32_16x16x32_bf16 v[100:103], v[148:151], v[204:207], v[100:103]
	v_mfma_f32_16x16x32_bf16 v[96:99], v[156:159], v[204:207], v[96:99]
	s_setprio 0
	s_setprio 1
	v_mfma_f32_16x16x32_bf16 v[92:95], v[160:163], v[176:179], v[92:95]
	v_mfma_f32_16x16x32_bf16 v[88:91], v[168:171], v[176:179], v[88:91]
	v_mfma_f32_16x16x32_bf16 v[84:87], v[160:163], v[184:187], v[84:87]
	v_mfma_f32_16x16x32_bf16 v[80:83], v[168:171], v[184:187], v[80:83]
	v_mfma_f32_16x16x32_bf16 v[76:79], v[160:163], v[192:195], v[76:79]
	v_mfma_f32_16x16x32_bf16 v[72:75], v[168:171], v[192:195], v[72:75]
	v_mfma_f32_16x16x32_bf16 v[68:71], v[160:163], v[200:203], v[68:71]
	v_mfma_f32_16x16x32_bf16 v[64:67], v[168:171], v[200:203], v[64:67]
	s_setprio 0
	s_setprio 1
	v_mfma_f32_16x16x32_bf16 v[92:95], v[164:167], v[180:183], v[92:95]
	v_mfma_f32_16x16x32_bf16 v[88:91], v[172:175], v[180:183], v[88:91]
	v_mfma_f32_16x16x32_bf16 v[84:87], v[164:167], v[188:191], v[84:87]
	v_mfma_f32_16x16x32_bf16 v[80:83], v[172:175], v[188:191], v[80:83]
	v_mfma_f32_16x16x32_bf16 v[76:79], v[164:167], v[196:199], v[76:79]
	v_mfma_f32_16x16x32_bf16 v[72:75], v[172:175], v[196:199], v[72:75]
	v_mfma_f32_16x16x32_bf16 v[68:71], v[164:167], v[204:207], v[68:71]
	v_mfma_f32_16x16x32_bf16 v[64:67], v[172:175], v[204:207], v[64:67]
	s_setprio 0
	s_barrier
; #define PG8_BAR __builtin_amdgcn_s_barrier()
; template <int ROT, class Epi0, class Epi1, class Late, class Post0>
; __device__ __forceinline__ void gemm_phase_pair(PG8_LAS unsigned char* lds, const Gemm g0, const Gemm g1, const Unit u, const Epi0& E0, const Epi1& E1, int wid_in, const Late& late, const Post0& post0) {
;     ...
;     }
;     if (ROT != 0) {
;         if (wr == 0) PG8_BAR;
	s_mov_b32 m0, s44
	v_lshl_add_u64 v[216:217], v[212:213], 0, s[28:29]
	ds_read_b128 v[176:179], v137 offset:49152
	ds_read_b128 v[180:183], v137 offset:50176
	ds_read_b128 v[184:187], v137 offset:51200
	ds_read_b128 v[188:191], v137 offset:52224
	ds_read_b128 v[192:195], v137 offset:53248
	ds_read_b128 v[196:199], v137 offset:54272
	ds_read_b128 v[200:203], v137 offset:55296
	ds_read_b128 v[204:207], v137 offset:56320
	global_load_lds_dwordx4 v[216:217], off
	v_lshl_add_u64 v[216:217], v[214:215], 0, s[28:29]
	s_mov_b32 m0, s42
	v_lshl_add_u64 v[212:213], v[212:213], 0, s[30:31]
	global_load_lds_dwordx4 v[216:217], off
	s_mov_b32 m0, s43
	v_lshl_add_u64 v[208:209], v[208:209], 0, s[36:37]
	global_load_lds_dwordx4 v[212:213], off
	v_lshl_add_u64 v[212:213], v[214:215], 0, s[30:31]
	s_mov_b32 m0, s41
	s_nop 0
	global_load_lds_dwordx4 v[212:213], off
	s_mov_b32 m0, s13
	s_nop 0
	global_load_lds_dwordx4 v[208:209], off
	v_lshl_add_u64 v[208:209], v[210:211], 0, s[36:37]
	s_mov_b32 m0, s33
	s_nop 0
	global_load_lds_dwordx4 v[208:209], off
	s_waitcnt vmcnt(8)
	s_waitcnt lgkmcnt(0)
	s_barrier
	s_setprio 1
	s_waitcnt lgkmcnt(0)
	v_mfma_f32_16x16x32_bf16 v[60:63], v[144:147], v[176:179], v[60:63]
	v_mfma_f32_16x16x32_bf16 v[56:59], v[152:155], v[176:179], v[56:59]
	v_mfma_f32_16x16x32_bf16 v[52:55], v[144:147], v[184:187], v[52:55]
	v_mfma_f32_16x16x32_bf16 v[48:51], v[152:155], v[184:187], v[48:51]
	v_mfma_f32_16x16x32_bf16 v[44:47], v[144:147], v[192:195], v[44:47]
	v_mfma_f32_16x16x32_bf16 v[40:43], v[152:155], v[192:195], v[40:43]
	v_mfma_f32_16x16x32_bf16 v[36:39], v[144:147], v[200:203], v[36:39]
	v_mfma_f32_16x16x32_bf16 v[32:35], v[152:155], v[200:203], v[32:35]
	s_setprio 0
	s_setprio 1
	v_mfma_f32_16x16x32_bf16 v[60:63], v[148:151], v[180:183], v[60:63]
	v_mfma_f32_16x16x32_bf16 v[56:59], v[156:159], v[180:183], v[56:59]
	v_mfma_f32_16x16x32_bf16 v[52:55], v[148:151], v[188:191], v[52:55]
	v_mfma_f32_16x16x32_bf16 v[48:51], v[156:159], v[188:191], v[48:51]
	v_mfma_f32_16x16x32_bf16 v[44:47], v[148:151], v[196:199], v[44:47]
	v_mfma_f32_16x16x32_bf16 v[40:43], v[156:159], v[196:199], v[40:43]
	v_mfma_f32_16x16x32_bf16 v[36:39], v[148:151], v[204:207], v[36:39]
	v_mfma_f32_16x16x32_bf16 v[32:35], v[156:159], v[204:207], v[32:35]
	s_setprio 0
	s_setprio 1
	v_mfma_f32_16x16x32_bf16 v[28:31], v[160:163], v[176:179], v[28:31]
	v_mfma_f32_16x16x32_bf16 v[24:27], v[168:171], v[176:179], v[24:27]
	v_mfma_f32_16x16x32_bf16 v[20:23], v[160:163], v[184:187], v[20:23]
	v_mfma_f32_16x16x32_bf16 v[16:19], v[168:171], v[184:187], v[16:19]
	v_mfma_f32_16x16x32_bf16 v[12:15], v[160:163], v[192:195], v[12:15]
	v_mfma_f32_16x16x32_bf16 v[8:11], v[168:171], v[192:195], v[8:11]
	v_mfma_f32_16x16x32_bf16 v[4:7], v[160:163], v[200:203], v[4:7]
	v_mfma_f32_16x16x32_bf16 v[0:3], v[168:171], v[200:203], v[0:3]
	s_setprio 0
	s_setprio 1
	v_mfma_f32_16x16x32_bf16 v[28:31], v[164:167], v[180:183], v[28:31]
	v_mfma_f32_16x16x32_bf16 v[24:27], v[172:175], v[180:183], v[24:27]
	v_mfma_f32_16x16x32_bf16 v[20:23], v[164:167], v[188:191], v[20:23]
	v_mfma_f32_16x16x32_bf16 v[16:19], v[172:175], v[188:191], v[16:19]
	v_mfma_f32_16x16x32_bf16 v[12:15], v[164:167], v[196:199], v[12:15]
	v_mfma_f32_16x16x32_bf16 v[8:11], v[172:175], v[196:199], v[8:11]
	v_mfma_f32_16x16x32_bf16 v[4:7], v[164:167], v[204:207], v[4:7]
	v_mfma_f32_16x16x32_bf16 v[0:3], v[172:175], v[204:207], v[0:3]
	s_setprio 0
	s_barrier
	s_add_i32 s53, s53, 2
	s_add_u32 s38, s38, 0x100
	s_addc_u32 s39, s39, 0
	s_cmp_gt_u32 s53, 11
	s_cbranch_scc0 .LBB0_847
	s_cmpk_lt_u32 s71, 0x100
	s_cselect_b64 s[4:5], -1, 0
	s_and_b64 vcc, exec, s[4:5]
	s_cbranch_vccz .LBB0_850
	s_barrier

; template <int ROT, class Epi0, class Epi1, class Late, class Post0>
; __device__ __forceinline__ void gemm_phase_pair(PG8_LAS unsigned char* lds, const Gemm g0, const Gemm g1, const Unit u, const Epi0& E0, const Epi1& E1, int wid_in, const Late& late, const Post0& post0) {
;     ...
;     for (int t = t_late; t < nt0 - 2; t += 2) {
;         if constexpr (Epi0::HAS_MID) { if (t == nt0 / 2) E0.mid(acc, u, wr, wc, fr, fq); }
;         const char* a1 = cA + PG8_KT(t + 1); const char* a2 = cA + PG8_KT(t + 2); const char* b2 = cB + PG8_KT(t + 2); const char* a3 = cA + PG8_KT(t + 3); const char* b3 = cB + PG8_KT(t + 3);
;         PG8_PAIR_ITER(a1 + hs0, vA0, a2, b2, a3, b3, vA0, vB0, hs0);
.LBB0_874:
	s_add_i32 s63, s18, 0xf80
	ds_read_b128 v[146:149], v141
	ds_read_b128 v[150:153], v141 offset:1024
	ds_read_b128 v[154:157], v141 offset:2048
	ds_read_b128 v[158:161], v141 offset:3072
	ds_read_b128 v[162:165], v140
	ds_read_b128 v[166:169], v140 offset:1024
	ds_read_b128 v[170:173], v140 offset:2048
	ds_read_b128 v[174:177], v140 offset:3072
	s_and_b32 s63, s63, 0xf80
	s_add_u32 s63, s16, s63
	s_addc_u32 s65, s17, 0
	s_add_u32 s64, s63, 0x80000
	s_mov_b32 m0, s51
	s_addc_u32 s65, s65, 0
	ds_read_b128 v[178:181], v137
	ds_read_b128 v[182:185], v137 offset:1024
	ds_read_b128 v[186:189], v137 offset:2048
	ds_read_b128 v[190:193], v137 offset:3072
	ds_read_b128 v[194:197], v137 offset:4096
	ds_read_b128 v[198:201], v137 offset:5120
	ds_read_b128 v[202:205], v137 offset:6144
	ds_read_b128 v[206:209], v137 offset:7168
	global_load_lds_dwordx4 v130, s[64:65]
	s_mov_b32 m0, s50
	v_mov_b32_e32 v129, v131
	global_load_lds_dwordx4 v128, s[64:65]
	s_waitcnt vmcnt(8)
	s_waitcnt lgkmcnt(0)
	s_barrier
	s_setprio 1
	s_waitcnt lgkmcnt(0)
	v_mfma_f32_16x16x32_bf16 v[124:127], v[146:149], v[178:181], v[124:127]
	v_mfma_f32_16x16x32_bf16 v[120:123], v[154:157], v[178:181], v[120:123]
	v_mfma_f32_16x16x32_bf16 v[116:119], v[146:149], v[186:189], v[116:119]
	v_mfma_f32_16x16x32_bf16 v[112:115], v[154:157], v[186:189], v[112:115]
	v_mfma_f32_16x16x32_bf16 v[108:111], v[146:149], v[194:197], v[108:111]
	v_mfma_f32_16x16x32_bf16 v[104:107], v[154:157], v[194:197], v[104:107]
	v_mfma_f32_16x16x32_bf16 v[100:103], v[146:149], v[202:205], v[100:103]
	v_mfma_f32_16x16x32_bf16 v[96:99], v[154:157], v[202:205], v[96:99]
	s_setprio 0
	s_setprio 1
	v_mfma_f32_16x16x32_bf16 v[124:127], v[150:153], v[182:185], v[124:127]
	v_mfma_f32_16x16x32_bf16 v[120:123], v[158:161], v[182:185], v[120:123]
	v_mfma_f32_16x16x32_bf16 v[116:119], v[150:153], v[190:193], v[116:119]
	v_mfma_f32_16x16x32_bf16 v[112:115], v[158:161], v[190:193], v[112:115]
	v_mfma_f32_16x16x32_bf16 v[108:111], v[150:153], v[198:201], v[108:111]
	v_mfma_f32_16x16x32_bf16 v[104:107], v[158:161], v[198:201], v[104:107]
	v_mfma_f32_16x16x32_bf16 v[100:103], v[150:153], v[206:209], v[100:103]
	v_mfma_f32_16x16x32_bf16 v[96:99], v[158:161], v[206:209], v[96:99]
	s_setprio 0
	s_setprio 1
	v_mfma_f32_16x16x32_bf16 v[92:95], v[162:165], v[178:181], v[92:95]
	v_mfma_f32_16x16x32_bf16 v[88:91], v[170:173], v[178:181], v[88:91]
	v_mfma_f32_16x16x32_bf16 v[84:87], v[162:165], v[186:189], v[84:87]
	v_mfma_f32_16x16x32_bf16 v[80:83], v[170:173], v[186:189], v[80:83]
	v_mfma_f32_16x16x32_bf16 v[76:79], v[162:165], v[194:197], v[76:79]
	v_mfma_f32_16x16x32_bf16 v[72:75], v[170:173], v[194:197], v[72:75]
	v_mfma_f32_16x16x32_bf16 v[68:71], v[162:165], v[202:205], v[68:71]
	v_mfma_f32_16x16x32_bf16 v[64:67], v[170:173], v[202:205], v[64:67]
	s_setprio 0
	s_setprio 1
	v_mfma_f32_16x16x32_bf16 v[92:95], v[166:169], v[182:185], v[92:95]
	v_mfma_f32_16x16x32_bf16 v[88:91], v[174:177], v[182:185], v[88:91]
	v_mfma_f32_16x16x32_bf16 v[84:87], v[166:169], v[190:193], v[84:87]
	v_mfma_f32_16x16x32_bf16 v[80:83], v[174:177], v[190:193], v[80:83]
	v_mfma_f32_16x16x32_bf16 v[76:79], v[166:169], v[198:201], v[76:79]
	v_mfma_f32_16x16x32_bf16 v[72:75], v[174:177], v[198:201], v[72:75]
	v_mfma_f32_16x16x32_bf16 v[68:71], v[166:169], v[206:209], v[68:71]
	v_mfma_f32_16x16x32_bf16 v[64:67], v[174:177], v[206:209], v[64:67]
	s_setprio 0
	s_barrier
	s_add_u32 s64, s38, s18
	v_mov_b32_e32 v133, v131
	s_addc_u32 s65, s39, s19
	v_lshl_add_u64 v[210:211], s[64:65], 0, v[132:133]
	s_mov_b32 m0, s49
	v_lshl_add_u64 v[212:213], v[210:211], 0, s[20:21]
	v_mov_b32_e32 v135, v131
	ds_read_b128 v[178:181], v137 offset:16384
	ds_read_b128 v[182:185], v137 offset:17408
	ds_read_b128 v[186:189], v137 offset:18432
	ds_read_b128 v[190:193], v137 offset:19456
	ds_read_b128 v[194:197], v137 offset:20480
	ds_read_b128 v[198:201], v137 offset:21504
	ds_read_b128 v[202:205], v137 offset:22528
	ds_read_b128 v[206:209], v137 offset:23552
	global_load_lds_dwordx4 v[212:213], off
	v_lshl_add_u64 v[212:213], s[64:65], 0, v[134:135]
	v_lshl_add_u64 v[214:215], v[212:213], 0, s[20:21]
	s_mov_b32 m0, s47
	s_add_u32 s64, s53, s18
	global_load_lds_dwordx4 v[214:215], off
	v_lshl_add_u64 v[214:215], v[210:211], 0, s[22:23]
	s_mov_b32 m0, s48
	s_addc_u32 s65, s61, s19
	global_load_lds_dwordx4 v[214:215], off
	v_lshl_add_u64 v[214:215], v[212:213], 0, s[22:23]
	s_mov_b32 m0, s46
	s_nop 0
	global_load_lds_dwordx4 v[214:215], off
	v_lshl_add_u64 v[214:215], s[64:65], 0, v[130:131]
	v_lshl_add_u64 v[216:217], v[214:215], 0, s[24:25]
	s_mov_b32 m0, s40
	s_nop 0
	global_load_lds_dwordx4 v[216:217], off
	v_lshl_add_u64 v[216:217], s[64:65], 0, v[128:129]
	v_lshl_add_u64 v[218:219], v[216:217], 0, s[24:25]
	s_mov_b32 m0, s45
	s_nop 0
	global_load_lds_dwordx4 v[218:219], off
	s_waitcnt vmcnt(8)
	s_waitcnt lgkmcnt(0)
	s_barrier
	s_setprio 1
	s_waitcnt lgkmcnt(0)
	v_mfma_f32_16x16x32_bf16 v[60:63], v[146:149], v[178:181], v[60:63]
	v_mfma_f32_16x16x32_bf16 v[56:59], v[154:157], v[178:181], v[56:59]
	v_mfma_f32_16x16x32_bf16 v[52:55], v[146:149], v[186:189], v[52:55]
	v_mfma_f32_16x16x32_bf16 v[48:51], v[154:157], v[186:189], v[48:51]
	v_mfma_f32_16x16x32_bf16 v[44:47], v[146:149], v[194:197], v[44:47]
	v_mfma_f32_16x16x32_bf16 v[40:43], v[154:157], v[194:197], v[40:43]
	v_mfma_f32_16x16x32_bf16 v[36:39], v[146:149], v[202:205], v[36:39]
	v_mfma_f32_16x16x32_bf16 v[32:35], v[154:157], v[202:205], v[32:35]
	s_setprio 0
	s_setprio 1
	v_mfma_f32_16x16x32_bf16 v[60:63], v[150:153], v[182:185], v[60:63]
	v_mfma_f32_16x16x32_bf16 v[56:59], v[158:161], v[182:185], v[56:59]
	v_mfma_f32_16x16x32_bf16 v[52:55], v[150:153], v[190:193], v[52:55]
	v_mfma_f32_16x16x32_bf16 v[48:51], v[158:161], v[190:193], v[48:51]
	v_mfma_f32_16x16x32_bf16 v[44:47], v[150:153], v[198:201], v[44:47]
	v_mfma_f32_16x16x32_bf16 v[40:43], v[158:161], v[198:201], v[40:43]
	v_mfma_f32_16x16x32_bf16 v[36:39], v[150:153], v[206:209], v[36:39]
	v_mfma_f32_16x16x32_bf16 v[32:35], v[158:161], v[206:209], v[32:35]
	s_setprio 0
	s_setprio 1
	v_mfma_f32_16x16x32_bf16 v[28:31], v[162:165], v[178:181], v[28:31]
	v_mfma_f32_16x16x32_bf16 v[24:27], v[170:173], v[178:181], v[24:27]
	v_mfma_f32_16x16x32_bf16 v[20:23], v[162:165], v[186:189], v[20:23]
	v_mfma_f32_16x16x32_bf16 v[16:19], v[170:173], v[186:189], v[16:19]
	v_mfma_f32_16x16x32_bf16 v[12:15], v[162:165], v[194:197], v[12:15]
	v_mfma_f32_16x16x32_bf16 v[8:11], v[170:173], v[194:197], v[8:11]
	v_mfma_f32_16x16x32_bf16 v[4:7], v[162:165], v[202:205], v[4:7]
	v_mfma_f32_16x16x32_bf16 v[0:3], v[170:173], v[202:205], v[0:3]
	s_setprio 0
	s_setprio 1
	v_mfma_f32_16x16x32_bf16 v[28:31], v[166:169], v[182:185], v[28:31]
	v_mfma_f32_16x16x32_bf16 v[24:27], v[174:177], v[182:185], v[24:27]
	v_mfma_f32_16x16x32_bf16 v[20:23], v[166:169], v[190:193], v[20:23]
	v_mfma_f32_16x16x32_bf16 v[16:19], v[174:177], v[190:193], v[16:19]
	v_mfma_f32_16x16x32_bf16 v[12:15], v[166:169], v[198:201], v[12:15]
	v_mfma_f32_16x16x32_bf16 v[8:11], v[174:177], v[198:201], v[8:11]
	v_mfma_f32_16x16x32_bf16 v[4:7], v[166:169], v[206:209], v[4:7]
	v_mfma_f32_16x16x32_bf16 v[0:3], v[174:177], v[206:209], v[0:3]
	s_setprio 0
	s_barrier
	ds_read_b128 v[146:149], v139
	ds_read_b128 v[150:153], v139 offset:1024
	ds_read_b128 v[154:157], v139 offset:2048
	ds_read_b128 v[158:161], v139 offset:3072
	ds_read_b128 v[162:165], v138
	ds_read_b128 v[166:169], v138 offset:1024
	ds_read_b128 v[170:173], v138 offset:2048
	ds_read_b128 v[174:177], v138 offset:3072
	s_mov_b32 m0, s34
	v_lshl_add_u64 v[218:219], v[214:215], 0, s[26:27]
	ds_read_b128 v[178:181], v137 offset:32768
	ds_read_b128 v[182:185], v137 offset:33792
	ds_read_b128 v[186:189], v137 offset:34816
	ds_read_b128 v[190:193], v137 offset:35840
	ds_read_b128 v[194:197], v137 offset:36864
	ds_read_b128 v[198:201], v137 offset:37888
	ds_read_b128 v[202:205], v137 offset:38912
	ds_read_b128 v[206:209], v137 offset:39936
	global_load_lds_dwordx4 v[218:219], off
	v_lshl_add_u64 v[218:219], v[216:217], 0, s[26:27]
	s_mov_b32 m0, s35
	s_nop 0
	global_load_lds_dwordx4 v[218:219], off
	s_waitcnt vmcnt(8)
	s_waitcnt lgkmcnt(0)
	s_barrier
	s_setprio 1
	s_waitcnt lgkmcnt(0)
	v_mfma_f32_16x16x32_bf16 v[124:127], v[146:149], v[178:181], v[124:127]
	v_mfma_f32_16x16x32_bf16 v[120:123], v[154:157], v[178:181], v[120:123]
	v_mfma_f32_16x16x32_bf16 v[116:119], v[146:149], v[186:189], v[116:119]
	v_mfma_f32_16x16x32_bf16 v[112:115], v[154:157], v[186:189], v[112:115]
	v_mfma_f32_16x16x32_bf16 v[108:111], v[146:149], v[194:197], v[108:111]
	v_mfma_f32_16x16x32_bf16 v[104:107], v[154:157], v[194:197], v[104:107]
	v_mfma_f32_16x16x32_bf16 v[100:103], v[146:149], v[202:205], v[100:103]
	v_mfma_f32_16x16x32_bf16 v[96:99], v[154:157], v[202:205], v[96:99]
	s_setprio 0
	s_setprio 1
	v_mfma_f32_16x16x32_bf16 v[124:127], v[150:153], v[182:185], v[124:127]
	v_mfma_f32_16x16x32_bf16 v[120:123], v[158:161], v[182:185], v[120:123]
	v_mfma_f32_16x16x32_bf16 v[116:119], v[150:153], v[190:193], v[116:119]
	v_mfma_f32_16x16x32_bf16 v[112:115], v[158:161], v[190:193], v[112:115]
	v_mfma_f32_16x16x32_bf16 v[108:111], v[150:153], v[198:201], v[108:111]
	v_mfma_f32_16x16x32_bf16 v[104:107], v[158:161], v[198:201], v[104:107]
	v_mfma_f32_16x16x32_bf16 v[100:103], v[150:153], v[206:209], v[100:103]
	v_mfma_f32_16x16x32_bf16 v[96:99], v[158:161], v[206:209], v[96:99]
	s_setprio 0
	s_setprio 1
	v_mfma_f32_16x16x32_bf16 v[92:95], v[162:165], v[178:181], v[92:95]
	v_mfma_f32_16x16x32_bf16 v[88:91], v[170:173], v[178:181], v[88:91]
	v_mfma_f32_16x16x32_bf16 v[84:87], v[162:165], v[186:189], v[84:87]
	v_mfma_f32_16x16x32_bf16 v[80:83], v[170:173], v[186:189], v[80:83]
	v_mfma_f32_16x16x32_bf16 v[76:79], v[162:165], v[194:197], v[76:79]
	v_mfma_f32_16x16x32_bf16 v[72:75], v[170:173], v[194:197], v[72:75]
	v_mfma_f32_16x16x32_bf16 v[68:71], v[162:165], v[202:205], v[68:71]
	v_mfma_f32_16x16x32_bf16 v[64:67], v[170:173], v[202:205], v[64:67]
	s_setprio 0
	s_setprio 1
	v_mfma_f32_16x16x32_bf16 v[92:95], v[166:169], v[182:185], v[92:95]
	v_mfma_f32_16x16x32_bf16 v[88:91], v[174:177], v[182:185], v[88:91]
	v_mfma_f32_16x16x32_bf16 v[84:87], v[166:169], v[190:193], v[84:87]
	v_mfma_f32_16x16x32_bf16 v[80:83], v[174:177], v[190:193], v[80:83]
	v_mfma_f32_16x16x32_bf16 v[76:79], v[166:169], v[198:201], v[76:79]
	v_mfma_f32_16x16x32_bf16 v[72:75], v[174:177], v[198:201], v[72:75]
	v_mfma_f32_16x16x32_bf16 v[68:71], v[166:169], v[206:209], v[68:71]
	v_mfma_f32_16x16x32_bf16 v[64:67], v[174:177], v[206:209], v[64:67]
	s_setprio 0
	s_barrier
	s_mov_b32 m0, s44
	v_lshl_add_u64 v[218:219], v[210:211], 0, s[28:29]
	ds_read_b128 v[178:181], v137 offset:49152
	ds_read_b128 v[182:185], v137 offset:50176
	ds_read_b128 v[186:189], v137 offset:51200
	ds_read_b128 v[190:193], v137 offset:52224
	ds_read_b128 v[194:197], v137 offset:53248
	ds_read_b128 v[198:201], v137 offset:54272
	ds_read_b128 v[202:205], v137 offset:55296
	ds_read_b128 v[206:209], v137 offset:56320
	global_load_lds_dwordx4 v[218:219], off
	v_lshl_add_u64 v[218:219], v[212:213], 0, s[28:29]
	s_mov_b32 m0, s42
	v_lshl_add_u64 v[210:211], v[210:211], 0, s[30:31]
	global_load_lds_dwordx4 v[218:219], off
	s_mov_b32 m0, s43
	s_nop 0
	global_load_lds_dwordx4 v[210:211], off
	v_lshl_add_u64 v[210:211], v[212:213], 0, s[30:31]
	s_mov_b32 m0, s41
	s_nop 0
	global_load_lds_dwordx4 v[210:211], off
	v_lshl_add_u64 v[210:211], v[214:215], 0, s[36:37]
	s_mov_b32 m0, s13
	s_nop 0
	global_load_lds_dwordx4 v[210:211], off
	v_lshl_add_u64 v[210:211], v[216:217], 0, s[36:37]
	s_mov_b32 m0, s33
	s_nop 0
	global_load_lds_dwordx4 v[210:211], off
	s_waitcnt vmcnt(8)
	s_waitcnt lgkmcnt(0)
	s_barrier
	s_setprio 1
	s_waitcnt lgkmcnt(0)
	v_mfma_f32_16x16x32_bf16 v[60:63], v[146:149], v[178:181], v[60:63]
	v_mfma_f32_16x16x32_bf16 v[56:59], v[154:157], v[178:181], v[56:59]
	v_mfma_f32_16x16x32_bf16 v[52:55], v[146:149], v[186:189], v[52:55]
	v_mfma_f32_16x16x32_bf16 v[48:51], v[154:157], v[186:189], v[48:51]
	v_mfma_f32_16x16x32_bf16 v[44:47], v[146:149], v[194:197], v[44:47]
	v_mfma_f32_16x16x32_bf16 v[40:43], v[154:157], v[194:197], v[40:43]
	v_mfma_f32_16x16x32_bf16 v[36:39], v[146:149], v[202:205], v[36:39]
	v_mfma_f32_16x16x32_bf16 v[32:35], v[154:157], v[202:205], v[32:35]
	s_setprio 0
	s_setprio 1
	v_mfma_f32_16x16x32_bf16 v[60:63], v[150:153], v[182:185], v[60:63]
	v_mfma_f32_16x16x32_bf16 v[56:59], v[158:161], v[182:185], v[56:59]
	v_mfma_f32_16x16x32_bf16 v[52:55], v[150:153], v[190:193], v[52:55]
	v_mfma_f32_16x16x32_bf16 v[48:51], v[158:161], v[190:193], v[48:51]
	v_mfma_f32_16x16x32_bf16 v[44:47], v[150:153], v[198:201], v[44:47]
	v_mfma_f32_16x16x32_bf16 v[40:43], v[158:161], v[198:201], v[40:43]
	v_mfma_f32_16x16x32_bf16 v[36:39], v[150:153], v[206:209], v[36:39]
	v_mfma_f32_16x16x32_bf16 v[32:35], v[158:161], v[206:209], v[32:35]
	s_setprio 0
	s_setprio 1
	v_mfma_f32_16x16x32_bf16 v[28:31], v[162:165], v[178:181], v[28:31]
	v_mfma_f32_16x16x32_bf16 v[24:27], v[170:173], v[178:181], v[24:27]
	v_mfma_f32_16x16x32_bf16 v[20:23], v[162:165], v[186:189], v[20:23]
	v_mfma_f32_16x16x32_bf16 v[16:19], v[170:173], v[186:189], v[16:19]
	v_mfma_f32_16x16x32_bf16 v[12:15], v[162:165], v[194:197], v[12:15]
	v_mfma_f32_16x16x32_bf16 v[8:11], v[170:173], v[194:197], v[8:11]
	v_mfma_f32_16x16x32_bf16 v[4:7], v[162:165], v[202:205], v[4:7]
	v_mfma_f32_16x16x32_bf16 v[0:3], v[170:173], v[202:205], v[0:3]
	s_setprio 0
	s_setprio 1
	v_mfma_f32_16x16x32_bf16 v[28:31], v[166:169], v[182:185], v[28:31]
	v_mfma_f32_16x16x32_bf16 v[24:27], v[174:177], v[182:185], v[24:27]
	v_mfma_f32_16x16x32_bf16 v[20:23], v[166:169], v[190:193], v[20:23]
	v_mfma_f32_16x16x32_bf16 v[16:19], v[174:177], v[190:193], v[16:19]
	v_mfma_f32_16x16x32_bf16 v[12:15], v[166:169], v[198:201], v[12:15]
	v_mfma_f32_16x16x32_bf16 v[8:11], v[174:177], v[198:201], v[8:11]
	v_mfma_f32_16x16x32_bf16 v[4:7], v[166:169], v[206:209], v[4:7]
	v_mfma_f32_16x16x32_bf16 v[0:3], v[174:177], v[206:209], v[0:3]
	s_setprio 0
	s_barrier
	s_add_i32 s62, s62, 2
	s_add_u32 s18, s18, 0x100
	s_addc_u32 s19, s19, 0
	s_cmp_gt_u32 s62, 27
	s_cbranch_scc1 .LBB0_877

.LBB0_877:
	v_mbcnt_lo_u32_b32 v129, -1, 0
	v_mbcnt_hi_u32_b32 v129, -1, v129
	s_mov_b32 s20, 0x7fffe0
	v_add_u32_e32 v129, s60, v129
	v_ashrrev_i32_e32 v132, 31, v129
	v_lshrrev_b32_e32 v132, 26, v132
	v_lshlrev_b32_e32 v131, 4, v129
	v_add_u32_e32 v132, v129, v132
	v_bfe_i32 v129, v129, 27, 1
	v_lshrrev_b32_e32 v129, 22, v129
	v_add_u32_e32 v129, v131, v129
	v_and_b32_e32 v129, 0xfffffc00, v129
	v_sub_u32_e32 v129, v131, v129
	v_lshrrev_b32_e32 v133, 4, v129
	v_bitop3_b32 v129, v133, v129, 32 bitop3:0x6c
	v_ashrrev_i32_e32 v134, 31, v129
	v_ashrrev_i32_e32 v132, 6, v132
	v_lshrrev_b32_e32 v134, 26, v134
	v_lshlrev_b32_e32 v133, 3, v132
	v_add_u32_e32 v134, v129, v134
	v_and_b32_e32 v133, -16, v133
	v_ashrrev_i32_e32 v135, 6, v134
	v_and_b32_e32 v134, 0xc0, v134
	v_add_u32_e32 v133, v135, v133
	v_sub_u32_e32 v129, v129, v134
	v_mov_b32_e32 v134, 1
	v_lshlrev_b32_e32 v132, 5, v132
	v_ashrrev_i16_sdwa v129, v134, sext(v129) dst_sel:DWORD dst_unused:UNUSED_PAD src0_sel:DWORD src1_sel:BYTE_0
	v_lshlrev_b32_e32 v144, 1, v133
	v_lshrrev_b32_e32 v145, 2, v133
	v_and_b32_e32 v135, 3, v135
	v_and_b32_e32 v132, 32, v132
	v_bfe_i32 v129, v129, 0, 16
	v_and_b32_e32 v144, 24, v144
	v_and_b32_e32 v145, 4, v145
	v_and_or_b32 v135, v133, s20, v135
	v_or3_b32 v135, v135, v145, v144
	v_add_lshl_u32 v129, v132, v129, 1
	v_lshl_add_u32 v228, v133, 9, v129
	v_lshl_add_u32 v132, v135, 9, v129
	v_add_u32_e32 v129, 0x2000, v131
	v_ashrrev_i32_e32 v131, 31, v129
	v_lshrrev_b32_e32 v131, 22, v131
	v_add_u32_e32 v131, v129, v131
	v_ashrrev_i32_e32 v131, 10, v131
	v_mul_i32_i24_e32 v133, 0x400, v131
	v_sub_u32_e32 v129, v129, v133
	v_lshrrev_b32_e32 v133, 4, v129
	v_bitop3_b32 v129, v133, v129, 32 bitop3:0x6c
	v_ashrrev_i32_e32 v135, 31, v129
	v_lshrrev_b32_e32 v135, 26, v135
	v_lshlrev_b32_e32 v133, 3, v131
	v_add_u32_e32 v135, v129, v135
	v_and_b32_e32 v133, -16, v133
	v_ashrrev_i32_e32 v144, 6, v135
	v_and_b32_e32 v135, 0xc0, v135
	v_add_u32_e32 v133, v144, v133
	v_sub_u32_e32 v129, v129, v135
	v_lshlrev_b32_e32 v131, 5, v131
	v_ashrrev_i16_sdwa v129, v134, sext(v129) dst_sel:DWORD dst_unused:UNUSED_PAD src0_sel:DWORD src1_sel:BYTE_0
	v_lshlrev_b32_e32 v134, 1, v133
	v_lshrrev_b32_e32 v135, 2, v133
	v_and_b32_e32 v144, 3, v144
	v_and_b32_e32 v131, 32, v131
	v_bfe_i32 v129, v129, 0, 16
	v_and_b32_e32 v134, 24, v134
	v_and_b32_e32 v135, 4, v135
	v_and_or_b32 v144, v133, s20, v144
	v_or3_b32 v134, v144, v135, v134
	v_add_lshl_u32 v129, v131, v129, 1
	v_lshl_add_u32 v230, v133, 9, v129
	v_lshl_add_u32 v134, v134, 9, v129
	ds_read_b128 v[144:147], v141
	ds_read_b128 v[148:151], v141 offset:1024
	ds_read_b128 v[152:155], v141 offset:2048
	ds_read_b128 v[156:159], v141 offset:3072
	ds_read_b128 v[160:163], v140
	ds_read_b128 v[164:167], v140 offset:1024
	ds_read_b128 v[168:171], v140 offset:2048
	ds_read_b128 v[172:175], v140 offset:3072
	s_lshl_b64 s[14:15], s[14:15], 17
	s_lshl_b64 s[18:19], s[8:9], 17
	s_add_u32 s9, s96, s14
	s_addc_u32 s21, s97, s15
	s_add_u32 s14, s9, 0x3400000
	s_addc_u32 s15, s21, 0
	s_add_u32 s22, s96, s18
	s_addc_u32 s23, s97, s19
	s_add_u32 s18, s22, 0x1300000
	s_addc_u32 s19, s23, 0
	s_add_u32 s16, s16, 0x80780
	s_addc_u32 s17, s17, 0
	s_mov_b32 m0, s51
	ds_read_b128 v[176:179], v137
	ds_read_b128 v[180:183], v137 offset:1024
	ds_read_b128 v[184:187], v137 offset:2048
	ds_read_b128 v[188:191], v137 offset:3072
	ds_read_b128 v[192:195], v137 offset:4096
	ds_read_b128 v[196:199], v137 offset:5120
	ds_read_b128 v[200:203], v137 offset:6144
	ds_read_b128 v[204:207], v137 offset:7168
	global_load_lds_dwordx4 v130, s[16:17]
	s_mov_b32 m0, s50
	s_nop 0
	global_load_lds_dwordx4 v128, s[16:17]
	s_waitcnt vmcnt(8)
	s_waitcnt lgkmcnt(0)
	s_barrier
	s_setprio 1
	s_waitcnt lgkmcnt(0)
	v_mfma_f32_16x16x32_bf16 v[124:127], v[144:147], v[176:179], v[124:127]
	v_mfma_f32_16x16x32_bf16 v[120:123], v[152:155], v[176:179], v[120:123]
	v_mfma_f32_16x16x32_bf16 v[116:119], v[144:147], v[184:187], v[116:119]
	v_mfma_f32_16x16x32_bf16 v[112:115], v[152:155], v[184:187], v[112:115]
	v_mfma_f32_16x16x32_bf16 v[100:103], v[144:147], v[200:203], v[100:103]
	v_mfma_f32_16x16x32_bf16 v[96:99], v[152:155], v[200:203], v[96:99]
	v_mfma_f32_16x16x32_bf16 v[124:127], v[148:151], v[180:183], v[124:127]
	v_mfma_f32_16x16x32_bf16 v[120:123], v[156:159], v[180:183], v[120:123]
	s_setprio 0
	s_setprio 1
	v_mfma_f32_16x16x32_bf16 v[116:119], v[148:151], v[188:191], v[116:119]
	v_mfma_f32_16x16x32_bf16 v[112:115], v[156:159], v[188:191], v[112:115]
	v_mfma_f32_16x16x32_bf16 v[108:111], v[144:147], v[192:195], v[108:111]
	v_mfma_f32_16x16x32_bf16 v[104:107], v[152:155], v[192:195], v[104:107]
	v_mfma_f32_16x16x32_bf16 v[100:103], v[148:151], v[204:207], v[100:103]
	v_mfma_f32_16x16x32_bf16 v[96:99], v[156:159], v[204:207], v[96:99]
	v_mfma_f32_16x16x32_bf16 v[128:131], v[148:151], v[196:199], v[108:111]
	v_mfma_f32_16x16x32_bf16 v[208:211], v[156:159], v[196:199], v[104:107]
	s_setprio 0
	s_setprio 1
	v_mfma_f32_16x16x32_bf16 v[84:87], v[160:163], v[184:187], v[84:87]
	v_mfma_f32_16x16x32_bf16 v[80:83], v[168:171], v[184:187], v[80:83]
	v_mfma_f32_16x16x32_bf16 v[68:71], v[160:163], v[200:203], v[68:71]
	v_mfma_f32_16x16x32_bf16 v[64:67], v[168:171], v[200:203], v[64:67]
	v_mfma_f32_16x16x32_bf16 v[92:95], v[160:163], v[176:179], v[92:95]
	v_mfma_f32_16x16x32_bf16 v[88:91], v[168:171], v[176:179], v[88:91]
	v_mfma_f32_16x16x32_bf16 v[84:87], v[164:167], v[188:191], v[84:87]
	v_mfma_f32_16x16x32_bf16 v[80:83], v[172:175], v[188:191], v[80:83]
	s_setprio 0
	s_setprio 1
	v_mfma_f32_16x16x32_bf16 v[76:79], v[160:163], v[192:195], v[76:79]
	v_mfma_f32_16x16x32_bf16 v[72:75], v[168:171], v[192:195], v[72:75]
	v_mfma_f32_16x16x32_bf16 v[68:71], v[164:167], v[204:207], v[68:71]
	v_mfma_f32_16x16x32_bf16 v[64:67], v[172:175], v[204:207], v[64:67]
	v_mfma_f32_16x16x32_bf16 v[212:215], v[164:167], v[180:183], v[92:95]
	v_mfma_f32_16x16x32_bf16 v[176:179], v[172:175], v[180:183], v[88:91]
	v_mfma_f32_16x16x32_bf16 v[180:183], v[164:167], v[196:199], v[76:79]
	v_mfma_f32_16x16x32_bf16 v[184:187], v[172:175], v[196:199], v[72:75]
	s_setprio 0
	s_barrier
	s_mov_b32 m0, s49
	ds_read_b128 v[72:75], v137 offset:16384
	ds_read_b128 v[76:79], v137 offset:17408
	ds_read_b128 v[88:91], v137 offset:18432
	ds_read_b128 v[92:95], v137 offset:19456
	ds_read_b128 v[104:107], v137 offset:20480
	ds_read_b128 v[108:111], v137 offset:21504
	ds_read_b128 v[188:191], v137 offset:22528
	ds_read_b128 v[192:195], v137 offset:23552
	global_load_lds_dwordx4 v132, s[18:19]
	s_mov_b32 m0, s47
	s_add_u32 s16, s22, 0x1310000
	global_load_lds_dwordx4 v134, s[18:19]
	s_addc_u32 s17, s23, 0
	s_mov_b32 m0, s48
	v_mov_b32_e32 v133, 0
	global_load_lds_dwordx4 v132, s[16:17]
	s_mov_b32 m0, s46
	v_mov_b32_e32 v135, v133
	global_load_lds_dwordx4 v134, s[16:17]
	s_mov_b32 m0, s40
	v_mov_b32_e32 v229, v133
	global_load_lds_dwordx4 v228, s[14:15]
	s_mov_b32 m0, s45
	v_mov_b32_e32 v231, v133
	global_load_lds_dwordx4 v230, s[14:15]
	s_waitcnt vmcnt(8)
	s_waitcnt lgkmcnt(0)
	v_lshl_add_u64 v[232:233], s[18:19], 0, v[132:133]
	v_lshl_add_u64 v[234:235], s[18:19], 0, v[134:135]
	v_lshl_add_u64 v[236:237], s[14:15], 0, v[228:229]
	v_lshl_add_u64 v[238:239], s[14:15], 0, v[230:231]
	s_barrier
	s_setprio 1
	s_waitcnt lgkmcnt(0)
	v_mfma_f32_16x16x32_bf16 v[52:55], v[144:147], v[88:91], v[52:55]
	v_mfma_f32_16x16x32_bf16 v[48:51], v[152:155], v[88:91], v[48:51]
	v_mfma_f32_16x16x32_bf16 v[36:39], v[144:147], v[188:191], v[36:39]
	v_mfma_f32_16x16x32_bf16 v[32:35], v[152:155], v[188:191], v[32:35]
	v_mfma_f32_16x16x32_bf16 v[60:63], v[144:147], v[72:75], v[60:63]
	v_mfma_f32_16x16x32_bf16 v[56:59], v[152:155], v[72:75], v[56:59]
	v_mfma_f32_16x16x32_bf16 v[52:55], v[148:151], v[92:95], v[52:55]
	v_mfma_f32_16x16x32_bf16 v[48:51], v[156:159], v[92:95], v[48:51]
	s_setprio 0
	s_setprio 1
	v_mfma_f32_16x16x32_bf16 v[44:47], v[144:147], v[104:107], v[44:47]
	v_mfma_f32_16x16x32_bf16 v[40:43], v[152:155], v[104:107], v[40:43]
	v_mfma_f32_16x16x32_bf16 v[36:39], v[148:151], v[192:195], v[36:39]
	v_mfma_f32_16x16x32_bf16 v[32:35], v[156:159], v[192:195], v[32:35]
	v_mfma_f32_16x16x32_bf16 v[196:199], v[148:151], v[76:79], v[60:63]
	v_mfma_f32_16x16x32_bf16 v[200:203], v[156:159], v[76:79], v[56:59]
	v_mfma_f32_16x16x32_bf16 v[204:207], v[148:151], v[108:111], v[44:47]
	v_mfma_f32_16x16x32_bf16 v[216:219], v[156:159], v[108:111], v[40:43]
	s_setprio 0
	s_setprio 1
	v_mfma_f32_16x16x32_bf16 v[20:23], v[160:163], v[88:91], v[20:23]
	v_mfma_f32_16x16x32_bf16 v[16:19], v[168:171], v[88:91], v[16:19]
	v_mfma_f32_16x16x32_bf16 v[4:7], v[160:163], v[188:191], v[4:7]
	v_mfma_f32_16x16x32_bf16 v[0:3], v[168:171], v[188:191], v[0:3]
	v_mfma_f32_16x16x32_bf16 v[28:31], v[160:163], v[72:75], v[28:31]
	v_mfma_f32_16x16x32_bf16 v[24:27], v[168:171], v[72:75], v[24:27]
	v_mfma_f32_16x16x32_bf16 v[20:23], v[164:167], v[92:95], v[20:23]
	v_mfma_f32_16x16x32_bf16 v[16:19], v[172:175], v[92:95], v[16:19]
	s_setprio 0
	s_setprio 1
	v_mfma_f32_16x16x32_bf16 v[12:15], v[160:163], v[104:107], v[12:15]
	v_mfma_f32_16x16x32_bf16 v[8:11], v[168:171], v[104:107], v[8:11]
	v_mfma_f32_16x16x32_bf16 v[4:7], v[164:167], v[192:195], v[4:7]
	v_mfma_f32_16x16x32_bf16 v[0:3], v[172:175], v[192:195], v[0:3]
	v_mfma_f32_16x16x32_bf16 v[144:147], v[164:167], v[76:79], v[28:31]
	v_mfma_f32_16x16x32_bf16 v[148:151], v[172:175], v[76:79], v[24:27]
	v_mfma_f32_16x16x32_bf16 v[152:155], v[164:167], v[108:111], v[12:15]
	v_mfma_f32_16x16x32_bf16 v[156:159], v[172:175], v[108:111], v[8:11]
	s_setprio 0
	s_barrier
	s_nop 0
	ds_read_b128 v[8:11], v139
	ds_read_b128 v[12:15], v139 offset:1024
	ds_read_b128 v[160:163], v139 offset:2048
	ds_read_b128 v[164:167], v139 offset:3072
	ds_read_b128 v[168:171], v138
	ds_read_b128 v[172:175], v138 offset:1024
	ds_read_b128 v[188:191], v138 offset:2048
	ds_read_b128 v[192:195], v138 offset:3072
	s_add_u32 s20, s9, 0x3410000
	s_addc_u32 s21, s21, 0
	s_mov_b32 m0, s34
	ds_read_b128 v[24:27], v137 offset:32768
	ds_read_b128 v[28:31], v137 offset:33792
	ds_read_b128 v[40:43], v137 offset:34816
	ds_read_b128 v[44:47], v137 offset:35840
	ds_read_b128 v[56:59], v137 offset:36864
	ds_read_b128 v[60:63], v137 offset:37888
	ds_read_b128 v[220:223], v137 offset:38912
	ds_read_b128 v[224:227], v137 offset:39936
	global_load_lds_dwordx4 v228, s[20:21]
	s_mov_b32 m0, s35
	s_nop 0
	global_load_lds_dwordx4 v230, s[20:21]
	s_waitcnt vmcnt(8)
	s_waitcnt lgkmcnt(0)
	s_barrier
; #define PG8_BAR __builtin_amdgcn_s_barrier()
; #define PG8_MK_V1(vA1, vB1) unsigned vA1[2], vB1[2]; { const int tid1_ = wid * 64 + hw_lane(); _Pragma("unroll") for (int i = 0; i < 2; ++i) { int R, C; stage_rc(tid1_ * 16 + i * 8192, R, C); \
;         const int Rb1 = Epi1::PERM ? ((R & ~31) + perm32(R & 31)) : R; vA1[i] = (unsigned)(R * K1 + C) * 2u; vB1[i] = (unsigned)(Rb1 * K1 + C) * 2u; } }
; template <int ROT, class Epi0, class Epi1, class Late, class Post0>
; __device__ __forceinline__ void gemm_phase_pair(PG8_LAS unsigned char* lds, const Gemm g0, const Gemm g1, const Unit u, const Epi0& E0, const Epi1& E1, int wid_in, const Late& late, const Post0& post0) {
;     ...
;     {
;         const char* a1 = cA + PG8_KT(nt0 - 1);
;         PG8_MK_V1(vA1x, vB1x)
;         PG8_PAIR_ITER(a1 + hs0, vA0, nA, nB, nA + kstep, nB + kstep, vA1x, vB1x, hs1);
;     }
;     ...
;     if (wr == 0) PG8_BAR;
	s_setprio 1
	s_waitcnt lgkmcnt(0)
	v_mfma_f32_16x16x32_bf16 v[72:75], v[8:11], v[24:27], v[124:127]
	v_mfma_f32_16x16x32_bf16 v[124:127], v[12:15], v[28:31], v[72:75]
	v_mfma_f32_16x16x32_bf16 v[72:75], v[160:163], v[24:27], v[120:123]
	v_mfma_f32_16x16x32_bf16 v[120:123], v[164:167], v[28:31], v[72:75]
	v_mfma_f32_16x16x32_bf16 v[72:75], v[8:11], v[40:43], v[116:119]
	v_mfma_f32_16x16x32_bf16 v[108:111], v[12:15], v[44:47], v[72:75]
	v_mfma_f32_16x16x32_bf16 v[72:75], v[160:163], v[40:43], v[112:115]
	v_mfma_f32_16x16x32_bf16 v[104:107], v[164:167], v[44:47], v[72:75]
	s_setprio 0
	s_setprio 1
	v_mfma_f32_16x16x32_bf16 v[72:75], v[8:11], v[56:59], v[128:131]
	v_mfma_f32_16x16x32_bf16 v[92:95], v[12:15], v[60:63], v[72:75]
	v_mfma_f32_16x16x32_bf16 v[72:75], v[160:163], v[56:59], v[208:211]
	v_mfma_f32_16x16x32_bf16 v[88:91], v[164:167], v[60:63], v[72:75]
	v_mfma_f32_16x16x32_bf16 v[72:75], v[8:11], v[220:223], v[100:103]
	v_mfma_f32_16x16x32_bf16 v[76:79], v[12:15], v[224:227], v[72:75]
	v_mfma_f32_16x16x32_bf16 v[72:75], v[160:163], v[220:223], v[96:99]
	v_mfma_f32_16x16x32_bf16 v[72:75], v[164:167], v[224:227], v[72:75]
	s_setprio 0
	s_setprio 1
	v_mfma_f32_16x16x32_bf16 v[96:99], v[168:171], v[24:27], v[212:215]
	v_mfma_f32_16x16x32_bf16 v[24:27], v[188:191], v[24:27], v[176:179]
	v_mfma_f32_16x16x32_bf16 v[116:119], v[192:195], v[28:31], v[24:27]
	v_mfma_f32_16x16x32_bf16 v[24:27], v[168:171], v[40:43], v[84:87]
	v_mfma_f32_16x16x32_bf16 v[112:115], v[172:175], v[28:31], v[96:99]
	v_mfma_f32_16x16x32_bf16 v[96:99], v[172:175], v[44:47], v[24:27]
	v_mfma_f32_16x16x32_bf16 v[24:27], v[188:191], v[40:43], v[80:83]
	v_mfma_f32_16x16x32_bf16 v[100:103], v[192:195], v[44:47], v[24:27]
	s_setprio 0
	s_setprio 1
	v_mfma_f32_16x16x32_bf16 v[24:27], v[168:171], v[56:59], v[180:183]
	v_mfma_f32_16x16x32_bf16 v[80:83], v[172:175], v[60:63], v[24:27]
	v_mfma_f32_16x16x32_bf16 v[24:27], v[188:191], v[56:59], v[184:187]
	v_mfma_f32_16x16x32_bf16 v[84:87], v[192:195], v[60:63], v[24:27]
	v_mfma_f32_16x16x32_bf16 v[24:27], v[168:171], v[220:223], v[68:71]
	v_mfma_f32_16x16x32_bf16 v[56:59], v[172:175], v[224:227], v[24:27]
	v_mfma_f32_16x16x32_bf16 v[24:27], v[188:191], v[220:223], v[64:67]
	v_mfma_f32_16x16x32_bf16 v[60:63], v[192:195], v[224:227], v[24:27]
	s_setprio 0
	s_barrier
	s_mov_b64 s[24:25], 0x80
	s_mov_b32 m0, s44
	s_nop 2
	v_lshl_add_u64 v[24:25], v[232:233], 0, s[24:25]
	ds_read_b128 v[128:131], v137 offset:49152
	ds_read_b128 v[176:179], v137 offset:50176
	ds_read_b128 v[180:183], v137 offset:51200
	ds_read_b128 v[184:187], v137 offset:52224
	ds_read_b128 v[208:211], v137 offset:53248
	ds_read_b128 v[212:215], v137 offset:54272
	ds_read_b128 v[220:223], v137 offset:55296
	ds_read_b128 v[224:227], v137 offset:56320
	global_load_lds_dwordx4 v[24:25], off
	v_lshl_add_u64 v[24:25], v[234:235], 0, s[24:25]
	s_mov_b32 m0, s42
	s_add_u32 s22, s22, 0x1310080
	global_load_lds_dwordx4 v[24:25], off
	s_addc_u32 s23, s23, 0
	s_mov_b32 m0, s43
	v_lshl_add_u64 v[24:25], v[236:237], 0, s[24:25]
	global_load_lds_dwordx4 v132, s[22:23]
	s_mov_b32 m0, s41
	s_nop 0
	global_load_lds_dwordx4 v134, s[22:23]
	s_mov_b32 m0, s13
	s_nop 0
	global_load_lds_dwordx4 v[24:25], off
	v_lshl_add_u64 v[24:25], v[238:239], 0, s[24:25]
	s_mov_b32 m0, s33
	s_nop 0
	global_load_lds_dwordx4 v[24:25], off
	s_waitcnt vmcnt(8)
	s_waitcnt lgkmcnt(0)
	s_barrier
	s_setprio 1
	s_waitcnt lgkmcnt(0)
	v_mfma_f32_16x16x32_bf16 v[24:27], v[8:11], v[128:131], v[196:199]
	v_mfma_f32_16x16x32_bf16 v[68:71], v[12:15], v[176:179], v[24:27]
	v_mfma_f32_16x16x32_bf16 v[24:27], v[160:163], v[128:131], v[200:203]
	v_mfma_f32_16x16x32_bf16 v[64:67], v[164:167], v[176:179], v[24:27]
	v_mfma_f32_16x16x32_bf16 v[24:27], v[8:11], v[180:183], v[52:55]
	v_mfma_f32_16x16x32_bf16 v[44:47], v[12:15], v[184:187], v[24:27]
	v_mfma_f32_16x16x32_bf16 v[24:27], v[160:163], v[180:183], v[48:51]
	v_mfma_f32_16x16x32_bf16 v[40:43], v[164:167], v[184:187], v[24:27]
	s_setprio 0
	s_setprio 1
	v_mfma_f32_16x16x32_bf16 v[24:27], v[8:11], v[208:211], v[204:207]
	v_mfma_f32_16x16x32_bf16 v[8:11], v[8:11], v[220:223], v[36:39]
	v_mfma_f32_16x16x32_bf16 v[28:31], v[12:15], v[212:215], v[24:27]
	v_mfma_f32_16x16x32_bf16 v[24:27], v[160:163], v[208:211], v[216:219]
	v_mfma_f32_16x16x32_bf16 v[12:15], v[12:15], v[224:227], v[8:11]
	v_mfma_f32_16x16x32_bf16 v[8:11], v[160:163], v[220:223], v[32:35]
	v_mfma_f32_16x16x32_bf16 v[24:27], v[164:167], v[212:215], v[24:27]
	v_mfma_f32_16x16x32_bf16 v[8:11], v[164:167], v[224:227], v[8:11]
	s_setprio 0
	s_setprio 1
	v_mfma_f32_16x16x32_bf16 v[32:35], v[168:171], v[128:131], v[144:147]
	v_mfma_f32_16x16x32_bf16 v[48:51], v[172:175], v[176:179], v[32:35]
	v_mfma_f32_16x16x32_bf16 v[32:35], v[188:191], v[128:131], v[148:151]
	v_mfma_f32_16x16x32_bf16 v[20:23], v[168:171], v[180:183], v[20:23]
	v_mfma_f32_16x16x32_bf16 v[16:19], v[188:191], v[180:183], v[16:19]
	v_mfma_f32_16x16x32_bf16 v[52:55], v[192:195], v[176:179], v[32:35]
	v_mfma_f32_16x16x32_bf16 v[32:35], v[172:175], v[184:187], v[20:23]
	v_mfma_f32_16x16x32_bf16 v[36:39], v[192:195], v[184:187], v[16:19]
	s_setprio 0
	s_setprio 1
	v_mfma_f32_16x16x32_bf16 v[16:19], v[168:171], v[208:211], v[152:155]
	v_mfma_f32_16x16x32_bf16 v[20:23], v[188:191], v[208:211], v[156:159]
	v_mfma_f32_16x16x32_bf16 v[4:7], v[168:171], v[220:223], v[4:7]
	v_mfma_f32_16x16x32_bf16 v[0:3], v[188:191], v[220:223], v[0:3]
	v_mfma_f32_16x16x32_bf16 v[16:19], v[172:175], v[212:215], v[16:19]
	v_mfma_f32_16x16x32_bf16 v[20:23], v[192:195], v[212:215], v[20:23]
	v_mfma_f32_16x16x32_bf16 v[4:7], v[172:175], v[224:227], v[4:7]
	v_mfma_f32_16x16x32_bf16 v[0:3], v[192:195], v[224:227], v[0:3]
	s_setprio 0
	s_barrier
	s_and_b64 vcc, exec, s[4:5]
	s_cbranch_vccz .LBB0_879
	s_barrier

.LBB0_886:
	v_mbcnt_lo_u32_b32 v0, -1, 0
	v_mbcnt_hi_u32_b32 v0, -1, v0
	v_mov_b32_e32 v6, 1
	v_add_u32_e32 v0, s60, v0
	v_ashrrev_i32_e32 v2, 31, v0
	v_lshrrev_b32_e32 v2, 26, v2
	v_lshlrev_b32_e32 v1, 4, v0
	v_add_u32_e32 v2, v0, v2
	v_bfe_i32 v0, v0, 27, 1
	v_lshrrev_b32_e32 v0, 22, v0
	v_add_u32_e32 v0, v1, v0
	v_and_b32_e32 v0, 0xfffffc00, v0
	v_sub_u32_e32 v0, v1, v0
	v_lshrrev_b32_e32 v3, 4, v0
	v_bitop3_b32 v0, v3, v0, 32 bitop3:0x6c
	v_ashrrev_i32_e32 v4, 31, v0
	v_lshrrev_b32_e32 v4, 26, v4
	v_add_u32_e32 v4, v0, v4
	v_ashrrev_i32_e32 v5, 6, v4
	v_and_b32_e32 v4, 0xc0, v4
	v_ashrrev_i32_e32 v2, 6, v2
	v_sub_u32_e32 v0, v0, v4
	v_lshlrev_b32_e32 v3, 3, v2
	v_lshlrev_b32_e32 v2, 5, v2
	v_ashrrev_i16_sdwa v0, v6, sext(v0) dst_sel:DWORD dst_unused:UNUSED_PAD src0_sel:DWORD src1_sel:BYTE_0
	v_and_b32_e32 v2, 32, v2
	v_bfe_i32 v0, v0, 0, 16
	v_add_u32_e32 v1, 0x2000, v1
	v_and_b32_e32 v3, -16, v3
	v_add_lshl_u32 v0, v2, v0, 1
	v_ashrrev_i32_e32 v2, 31, v1
	v_add_u32_e32 v3, v5, v3
	v_lshrrev_b32_e32 v2, 22, v2
	v_lshlrev_b32_e32 v4, 1, v3
	v_lshrrev_b32_e32 v7, 2, v3
	v_and_b32_e32 v5, 3, v5
	s_mov_b32 s0, 0x7fffe0
	v_add_u32_e32 v2, v1, v2
	v_and_b32_e32 v4, 24, v4
	v_and_b32_e32 v7, 4, v7
	v_and_or_b32 v5, v3, s0, v5
	v_ashrrev_i32_e32 v2, 10, v2
	v_or3_b32 v5, v5, v7, v4
	v_lshl_add_u32 v4, v3, 9, v0
	v_mul_i32_i24_e32 v3, 0x400, v2
	v_sub_u32_e32 v1, v1, v3
	v_lshrrev_b32_e32 v3, 4, v1
	v_bitop3_b32 v1, v3, v1, 32 bitop3:0x6c
	v_lshl_add_u32 v0, v5, 9, v0
	v_ashrrev_i32_e32 v5, 31, v1
	v_lshrrev_b32_e32 v5, 26, v5
	v_add_u32_e32 v5, v1, v5
	v_lshlrev_b32_e32 v3, 3, v2
	v_ashrrev_i32_e32 v7, 6, v5
	v_and_b32_e32 v5, 0xc0, v5
	v_and_b32_e32 v3, -16, v3
	v_sub_u32_e32 v1, v1, v5
	v_add_u32_e32 v3, v7, v3
	v_lshlrev_b32_e32 v2, 5, v2
	v_ashrrev_i16_sdwa v1, v6, sext(v1) dst_sel:DWORD dst_unused:UNUSED_PAD src0_sel:DWORD src1_sel:BYTE_0
	v_and_b32_e32 v2, 32, v2
	v_bfe_i32 v1, v1, 0, 16
	v_lshlrev_b32_e32 v5, 1, v3
	v_lshrrev_b32_e32 v6, 2, v3
	v_and_b32_e32 v7, 3, v7
	v_and_b32_e32 v5, 24, v5
	v_and_b32_e32 v6, 4, v6
	v_and_or_b32 v7, v3, s0, v7
	v_add_lshl_u32 v1, v2, v1, 1
	v_or3_b32 v5, v7, v6, v5
	v_lshl_add_u32 v6, v3, 9, v1
	v_lshl_add_u32 v2, v5, 9, v1
	s_add_u32 s10, s18, 0x10100
	ds_read_b128 v[8:11], v141
	ds_read_b128 v[12:15], v141 offset:1024
	ds_read_b128 v[16:19], v141 offset:2048
	ds_read_b128 v[20:23], v141 offset:3072
	ds_read_b128 v[24:27], v140
	ds_read_b128 v[28:31], v140 offset:1024
	ds_read_b128 v[32:35], v140 offset:2048
	ds_read_b128 v[36:39], v140 offset:3072
	s_addc_u32 s11, s19, 0
	s_add_u32 s8, s14, 0x10100
	s_addc_u32 s9, s15, 0
	s_add_u32 s0, s18, 0x10180
	s_addc_u32 s1, s19, 0
	s_add_u32 s24, s14, 0x10080
	s_mov_b32 m0, s51
	s_addc_u32 s25, s15, 0
	ds_read_b128 v[40:43], v137
	ds_read_b128 v[44:47], v137 offset:1024
	ds_read_b128 v[48:51], v137 offset:2048
	ds_read_b128 v[52:55], v137 offset:3072
	ds_read_b128 v[56:59], v137 offset:4096
	ds_read_b128 v[60:63], v137 offset:5120
	ds_read_b128 v[64:67], v137 offset:6144
	ds_read_b128 v[68:71], v137 offset:7168
	global_load_lds_dwordx4 v4, s[24:25]
	s_mov_b32 m0, s50
	v_mov_b32_e32 v5, 0
	global_load_lds_dwordx4 v6, s[24:25]
	s_waitcnt vmcnt(8)
	s_waitcnt lgkmcnt(0)
	v_mov_b32_e32 v7, v5
	s_barrier
	s_setprio 1
	s_waitcnt lgkmcnt(0)
	v_mfma_f32_16x16x32_bf16 v[72:75], v[8:11], v[40:43], 0
	v_mfma_f32_16x16x32_bf16 v[76:79], v[16:19], v[40:43], 0
	v_mfma_f32_16x16x32_bf16 v[80:83], v[8:11], v[48:51], 0
	v_mfma_f32_16x16x32_bf16 v[84:87], v[16:19], v[48:51], 0
	v_mfma_f32_16x16x32_bf16 v[88:91], v[8:11], v[56:59], 0
	v_mfma_f32_16x16x32_bf16 v[92:95], v[16:19], v[56:59], 0
	v_mfma_f32_16x16x32_bf16 v[96:99], v[8:11], v[64:67], 0
	v_mfma_f32_16x16x32_bf16 v[100:103], v[16:19], v[64:67], 0
	s_setprio 0
	s_setprio 1
	v_mfma_f32_16x16x32_bf16 v[72:75], v[12:15], v[44:47], v[72:75]
	v_mfma_f32_16x16x32_bf16 v[76:79], v[20:23], v[44:47], v[76:79]
	v_mfma_f32_16x16x32_bf16 v[80:83], v[12:15], v[52:55], v[80:83]
	v_mfma_f32_16x16x32_bf16 v[84:87], v[20:23], v[52:55], v[84:87]
	v_mfma_f32_16x16x32_bf16 v[88:91], v[12:15], v[60:63], v[88:91]
	v_mfma_f32_16x16x32_bf16 v[92:95], v[20:23], v[60:63], v[92:95]
	v_mfma_f32_16x16x32_bf16 v[96:99], v[12:15], v[68:71], v[96:99]
	v_mfma_f32_16x16x32_bf16 v[100:103], v[20:23], v[68:71], v[100:103]
	s_setprio 0
	s_setprio 1
	v_mfma_f32_16x16x32_bf16 v[104:107], v[24:27], v[40:43], 0
	v_mfma_f32_16x16x32_bf16 v[40:43], v[32:35], v[40:43], 0
	v_mfma_f32_16x16x32_bf16 v[104:107], v[28:31], v[44:47], v[104:107]
	v_mfma_f32_16x16x32_bf16 v[40:43], v[36:39], v[44:47], v[40:43]
	v_mfma_f32_16x16x32_bf16 v[44:47], v[24:27], v[48:51], 0
	v_mfma_f32_16x16x32_bf16 v[48:51], v[32:35], v[48:51], 0
	v_mfma_f32_16x16x32_bf16 v[44:47], v[28:31], v[52:55], v[44:47]
	v_mfma_f32_16x16x32_bf16 v[48:51], v[36:39], v[52:55], v[48:51]
	s_setprio 0
	s_setprio 1
	v_mfma_f32_16x16x32_bf16 v[52:55], v[24:27], v[56:59], 0
	v_mfma_f32_16x16x32_bf16 v[56:59], v[32:35], v[56:59], 0
	v_mfma_f32_16x16x32_bf16 v[52:55], v[28:31], v[60:63], v[52:55]
	v_mfma_f32_16x16x32_bf16 v[56:59], v[36:39], v[60:63], v[56:59]
	v_mfma_f32_16x16x32_bf16 v[60:63], v[24:27], v[64:67], 0
	v_mfma_f32_16x16x32_bf16 v[64:67], v[32:35], v[64:67], 0
	v_mfma_f32_16x16x32_bf16 v[60:63], v[28:31], v[68:71], v[60:63]
	v_mfma_f32_16x16x32_bf16 v[64:67], v[36:39], v[68:71], v[64:67]
	s_setprio 0
	s_barrier
	v_mov_b32_e32 v1, v5
	v_lshl_add_u64 v[134:135], s[18:19], 0, v[0:1]
	s_mov_b64 s[24:25], 0x100
	v_mov_b32_e32 v3, v5
	s_mov_b32 m0, s49
	v_lshl_add_u64 v[146:147], v[134:135], 0, s[24:25]
	v_lshl_add_u64 v[210:211], s[18:19], 0, v[2:3]
	ds_read_b128 v[68:71], v137 offset:16384
	ds_read_b128 v[108:111], v137 offset:17408
	ds_read_b128 v[112:115], v137 offset:18432
	ds_read_b128 v[116:119], v137 offset:19456
	ds_read_b128 v[120:123], v137 offset:20480
	ds_read_b128 v[124:127], v137 offset:21504
	ds_read_b128 v[130:133], v137 offset:22528
	ds_read_b128 v[142:145], v137 offset:23552
	global_load_lds_dwordx4 v[146:147], off
	v_lshl_add_u64 v[146:147], v[210:211], 0, s[24:25]
	s_mov_b32 m0, s47
	v_lshl_add_u64 v[212:213], s[14:15], 0, v[4:5]
	global_load_lds_dwordx4 v[146:147], off
	s_mov_b32 m0, s48
	v_lshl_add_u64 v[146:147], v[212:213], 0, s[24:25]
	global_load_lds_dwordx4 v0, s[10:11]
	s_mov_b32 m0, s46
	v_lshl_add_u64 v[214:215], s[14:15], 0, v[6:7]
	global_load_lds_dwordx4 v2, s[10:11]
	s_mov_b32 m0, s40
	s_nop 0
	global_load_lds_dwordx4 v[146:147], off
	v_lshl_add_u64 v[146:147], v[214:215], 0, s[24:25]
	s_mov_b32 m0, s45
	s_nop 0
	global_load_lds_dwordx4 v[146:147], off
	s_waitcnt vmcnt(8)
	s_waitcnt lgkmcnt(0)
	s_barrier
	s_setprio 1
	s_waitcnt lgkmcnt(0)
	v_mfma_f32_16x16x32_bf16 v[146:149], v[8:11], v[68:71], 0
	v_mfma_f32_16x16x32_bf16 v[154:157], v[8:11], v[112:115], 0
	v_mfma_f32_16x16x32_bf16 v[162:165], v[8:11], v[120:123], 0
	v_mfma_f32_16x16x32_bf16 v[8:11], v[8:11], v[130:133], 0
	v_mfma_f32_16x16x32_bf16 v[146:149], v[12:15], v[108:111], v[146:149]
	v_mfma_f32_16x16x32_bf16 v[154:157], v[12:15], v[116:119], v[154:157]
	v_mfma_f32_16x16x32_bf16 v[162:165], v[12:15], v[124:127], v[162:165]
	v_mfma_f32_16x16x32_bf16 v[8:11], v[12:15], v[142:145], v[8:11]
	s_setprio 0
	s_setprio 1
	v_mfma_f32_16x16x32_bf16 v[12:15], v[16:19], v[130:133], 0
	v_mfma_f32_16x16x32_bf16 v[150:153], v[16:19], v[68:71], 0
	v_mfma_f32_16x16x32_bf16 v[158:161], v[16:19], v[112:115], 0
	v_mfma_f32_16x16x32_bf16 v[166:169], v[16:19], v[120:123], 0
	v_mfma_f32_16x16x32_bf16 v[12:15], v[20:23], v[142:145], v[12:15]
	v_mfma_f32_16x16x32_bf16 v[150:153], v[20:23], v[108:111], v[150:153]
	v_mfma_f32_16x16x32_bf16 v[158:161], v[20:23], v[116:119], v[158:161]
	v_mfma_f32_16x16x32_bf16 v[166:169], v[20:23], v[124:127], v[166:169]
	s_setprio 0
	s_setprio 1
	v_mfma_f32_16x16x32_bf16 v[16:19], v[24:27], v[68:71], 0
	v_mfma_f32_16x16x32_bf16 v[20:23], v[32:35], v[68:71], 0
	v_mfma_f32_16x16x32_bf16 v[16:19], v[28:31], v[108:111], v[16:19]
	v_mfma_f32_16x16x32_bf16 v[20:23], v[36:39], v[108:111], v[20:23]
	v_mfma_f32_16x16x32_bf16 v[68:71], v[24:27], v[112:115], 0
	v_mfma_f32_16x16x32_bf16 v[108:111], v[32:35], v[112:115], 0
	v_mfma_f32_16x16x32_bf16 v[112:115], v[24:27], v[120:123], 0
	v_mfma_f32_16x16x32_bf16 v[24:27], v[24:27], v[130:133], 0
	s_setprio 0
	s_setprio 1
	v_mfma_f32_16x16x32_bf16 v[68:71], v[28:31], v[116:119], v[68:71]
	v_mfma_f32_16x16x32_bf16 v[108:111], v[36:39], v[116:119], v[108:111]
	v_mfma_f32_16x16x32_bf16 v[112:115], v[28:31], v[124:127], v[112:115]
	v_mfma_f32_16x16x32_bf16 v[116:119], v[32:35], v[120:123], 0
	v_mfma_f32_16x16x32_bf16 v[24:27], v[28:31], v[142:145], v[24:27]
	v_mfma_f32_16x16x32_bf16 v[28:31], v[32:35], v[130:133], 0
	v_mfma_f32_16x16x32_bf16 v[116:119], v[36:39], v[124:127], v[116:119]
	v_mfma_f32_16x16x32_bf16 v[28:31], v[36:39], v[142:145], v[28:31]
	s_setprio 0
	s_barrier
	ds_read_b128 v[32:35], v139
	ds_read_b128 v[36:39], v139 offset:1024
	ds_read_b128 v[120:123], v139 offset:2048
	ds_read_b128 v[124:127], v139 offset:3072
	ds_read_b128 v[130:133], v138
	ds_read_b128 v[142:145], v138 offset:1024
	ds_read_b128 v[170:173], v138 offset:2048
	ds_read_b128 v[174:177], v138 offset:3072
	s_mov_b32 m0, s34
	ds_read_b128 v[178:181], v137 offset:32768
	ds_read_b128 v[182:185], v137 offset:33792
	ds_read_b128 v[186:189], v137 offset:34816
	ds_read_b128 v[190:193], v137 offset:35840
	ds_read_b128 v[194:197], v137 offset:36864
	ds_read_b128 v[198:201], v137 offset:37888
	ds_read_b128 v[202:205], v137 offset:38912
	ds_read_b128 v[206:209], v137 offset:39936
	global_load_lds_dwordx4 v4, s[8:9]
	s_mov_b32 m0, s35
	s_nop 0
	global_load_lds_dwordx4 v6, s[8:9]
	s_waitcnt vmcnt(8)
	s_waitcnt lgkmcnt(0)
	s_barrier
	s_setprio 1
	s_waitcnt lgkmcnt(0)
	v_mfma_f32_16x16x32_bf16 v[72:75], v[32:35], v[178:181], v[72:75]
	v_mfma_f32_16x16x32_bf16 v[76:79], v[120:123], v[178:181], v[76:79]
	v_mfma_f32_16x16x32_bf16 v[80:83], v[32:35], v[186:189], v[80:83]
	v_mfma_f32_16x16x32_bf16 v[84:87], v[120:123], v[186:189], v[84:87]
	v_mfma_f32_16x16x32_bf16 v[88:91], v[32:35], v[194:197], v[88:91]
	v_mfma_f32_16x16x32_bf16 v[92:95], v[120:123], v[194:197], v[92:95]
	v_mfma_f32_16x16x32_bf16 v[96:99], v[32:35], v[202:205], v[96:99]
	v_mfma_f32_16x16x32_bf16 v[100:103], v[120:123], v[202:205], v[100:103]
	s_setprio 0
	s_setprio 1
	v_mfma_f32_16x16x32_bf16 v[72:75], v[36:39], v[182:185], v[72:75]
	v_mfma_f32_16x16x32_bf16 v[76:79], v[124:127], v[182:185], v[76:79]
	v_mfma_f32_16x16x32_bf16 v[80:83], v[36:39], v[190:193], v[80:83]
	v_mfma_f32_16x16x32_bf16 v[84:87], v[124:127], v[190:193], v[84:87]
	v_mfma_f32_16x16x32_bf16 v[88:91], v[36:39], v[198:201], v[88:91]
	v_mfma_f32_16x16x32_bf16 v[92:95], v[124:127], v[198:201], v[92:95]
	v_mfma_f32_16x16x32_bf16 v[96:99], v[36:39], v[206:209], v[96:99]
	v_mfma_f32_16x16x32_bf16 v[100:103], v[124:127], v[206:209], v[100:103]
	s_setprio 0
	s_setprio 1
	v_mfma_f32_16x16x32_bf16 v[104:107], v[130:133], v[178:181], v[104:107]
	v_mfma_f32_16x16x32_bf16 v[40:43], v[170:173], v[178:181], v[40:43]
	v_mfma_f32_16x16x32_bf16 v[44:47], v[130:133], v[186:189], v[44:47]
	v_mfma_f32_16x16x32_bf16 v[48:51], v[170:173], v[186:189], v[48:51]
	v_mfma_f32_16x16x32_bf16 v[52:55], v[130:133], v[194:197], v[52:55]
	v_mfma_f32_16x16x32_bf16 v[56:59], v[170:173], v[194:197], v[56:59]
	v_mfma_f32_16x16x32_bf16 v[60:63], v[130:133], v[202:205], v[60:63]
	v_mfma_f32_16x16x32_bf16 v[64:67], v[170:173], v[202:205], v[64:67]
	s_setprio 0
	s_setprio 1
	v_mfma_f32_16x16x32_bf16 v[104:107], v[142:145], v[182:185], v[104:107]
	v_mfma_f32_16x16x32_bf16 v[40:43], v[174:177], v[182:185], v[40:43]
	v_mfma_f32_16x16x32_bf16 v[44:47], v[142:145], v[190:193], v[44:47]
	v_mfma_f32_16x16x32_bf16 v[48:51], v[174:177], v[190:193], v[48:51]
	v_mfma_f32_16x16x32_bf16 v[52:55], v[142:145], v[198:201], v[52:55]
	v_mfma_f32_16x16x32_bf16 v[56:59], v[174:177], v[198:201], v[56:59]
	v_mfma_f32_16x16x32_bf16 v[60:63], v[142:145], v[206:209], v[60:63]
	v_mfma_f32_16x16x32_bf16 v[64:67], v[174:177], v[206:209], v[64:67]
	s_setprio 0
	s_barrier
	s_mov_b64 s[8:9], 0x180
	s_mov_b32 m0, s44
	v_lshl_add_u64 v[134:135], v[134:135], 0, s[8:9]
	ds_read_b128 v[178:181], v137 offset:49152
	ds_read_b128 v[182:185], v137 offset:50176
	ds_read_b128 v[186:189], v137 offset:51200
	ds_read_b128 v[190:193], v137 offset:52224
	ds_read_b128 v[194:197], v137 offset:53248
	ds_read_b128 v[198:201], v137 offset:54272
	ds_read_b128 v[202:205], v137 offset:55296
	ds_read_b128 v[206:209], v137 offset:56320
	global_load_lds_dwordx4 v[134:135], off
	v_lshl_add_u64 v[134:135], v[210:211], 0, s[8:9]
	s_mov_b32 m0, s42
	s_nop 0
	global_load_lds_dwordx4 v[134:135], off
	s_mov_b32 m0, s43
	v_lshl_add_u64 v[134:135], v[212:213], 0, s[8:9]
	global_load_lds_dwordx4 v0, s[0:1]
	s_mov_b32 m0, s41
	s_nop 0
	global_load_lds_dwordx4 v2, s[0:1]
	s_mov_b32 m0, s13
	s_nop 0
	global_load_lds_dwordx4 v[134:135], off
	v_lshl_add_u64 v[134:135], v[214:215], 0, s[8:9]
	s_mov_b32 m0, s33
	s_nop 0
	global_load_lds_dwordx4 v[134:135], off
	s_waitcnt vmcnt(8)
	s_waitcnt lgkmcnt(0)
	s_barrier
	s_setprio 1
	s_waitcnt lgkmcnt(0)
	v_mfma_f32_16x16x32_bf16 v[8:11], v[32:35], v[202:205], v[8:11]
	v_mfma_f32_16x16x32_bf16 v[12:15], v[120:123], v[202:205], v[12:15]
	v_mfma_f32_16x16x32_bf16 v[146:149], v[32:35], v[178:181], v[146:149]
	v_mfma_f32_16x16x32_bf16 v[150:153], v[120:123], v[178:181], v[150:153]
	v_mfma_f32_16x16x32_bf16 v[154:157], v[32:35], v[186:189], v[154:157]
	v_mfma_f32_16x16x32_bf16 v[158:161], v[120:123], v[186:189], v[158:161]
	v_mfma_f32_16x16x32_bf16 v[162:165], v[32:35], v[194:197], v[162:165]
	v_mfma_f32_16x16x32_bf16 v[166:169], v[120:123], v[194:197], v[166:169]
	s_setprio 0
	s_setprio 1
	v_mfma_f32_16x16x32_bf16 v[8:11], v[36:39], v[206:209], v[8:11]
	v_mfma_f32_16x16x32_bf16 v[12:15], v[124:127], v[206:209], v[12:15]
	v_mfma_f32_16x16x32_bf16 v[146:149], v[36:39], v[182:185], v[146:149]
	v_mfma_f32_16x16x32_bf16 v[150:153], v[124:127], v[182:185], v[150:153]
	v_mfma_f32_16x16x32_bf16 v[154:157], v[36:39], v[190:193], v[154:157]
	v_mfma_f32_16x16x32_bf16 v[158:161], v[124:127], v[190:193], v[158:161]
	v_mfma_f32_16x16x32_bf16 v[162:165], v[36:39], v[198:201], v[162:165]
	v_mfma_f32_16x16x32_bf16 v[166:169], v[124:127], v[198:201], v[166:169]
	s_setprio 0
	s_setprio 1
	v_mfma_f32_16x16x32_bf16 v[16:19], v[130:133], v[178:181], v[16:19]
	v_mfma_f32_16x16x32_bf16 v[20:23], v[170:173], v[178:181], v[20:23]
	v_mfma_f32_16x16x32_bf16 v[32:35], v[130:133], v[186:189], v[68:71]
	v_mfma_f32_16x16x32_bf16 v[36:39], v[170:173], v[186:189], v[108:111]
	v_mfma_f32_16x16x32_bf16 v[68:71], v[130:133], v[194:197], v[112:115]
	v_mfma_f32_16x16x32_bf16 v[108:111], v[170:173], v[194:197], v[116:119]
	v_mfma_f32_16x16x32_bf16 v[24:27], v[130:133], v[202:205], v[24:27]
	v_mfma_f32_16x16x32_bf16 v[28:31], v[170:173], v[202:205], v[28:31]
	s_setprio 0
	s_setprio 1
	v_mfma_f32_16x16x32_bf16 v[16:19], v[142:145], v[182:185], v[16:19]
	v_mfma_f32_16x16x32_bf16 v[20:23], v[174:177], v[182:185], v[20:23]
	v_mfma_f32_16x16x32_bf16 v[32:35], v[142:145], v[190:193], v[32:35]
	v_mfma_f32_16x16x32_bf16 v[36:39], v[174:177], v[190:193], v[36:39]
	v_mfma_f32_16x16x32_bf16 v[68:71], v[142:145], v[198:201], v[68:71]
	v_mfma_f32_16x16x32_bf16 v[108:111], v[174:177], v[198:201], v[108:111]
	v_mfma_f32_16x16x32_bf16 v[24:27], v[142:145], v[206:209], v[24:27]
	v_mfma_f32_16x16x32_bf16 v[28:31], v[174:177], v[206:209], v[28:31]
	s_setprio 0
	s_barrier
	s_nop 0
	ds_read_b128 v[112:115], v141
	ds_read_b128 v[116:119], v141 offset:1024
	ds_read_b128 v[120:123], v141 offset:2048
	ds_read_b128 v[124:127], v141 offset:3072
	ds_read_b128 v[130:133], v140
	ds_read_b128 v[142:145], v140 offset:1024
	ds_read_b128 v[170:173], v140 offset:2048
	ds_read_b128 v[174:177], v140 offset:3072
	s_add_u32 s0, s14, 0x10180
	s_mov_b32 m0, s51
	s_addc_u32 s1, s15, 0
	ds_read_b128 v[178:181], v137
	ds_read_b128 v[182:185], v137 offset:1024
	ds_read_b128 v[186:189], v137 offset:2048
	ds_read_b128 v[190:193], v137 offset:3072
	ds_read_b128 v[194:197], v137 offset:4096
	ds_read_b128 v[198:201], v137 offset:5120
	ds_read_b128 v[202:205], v137 offset:6144
	ds_read_b128 v[206:209], v137 offset:7168
	global_load_lds_dwordx4 v4, s[0:1]
	s_mov_b32 m0, s50
	s_nop 0
	global_load_lds_dwordx4 v6, s[0:1]
	s_waitcnt vmcnt(8)
	s_waitcnt lgkmcnt(0)
	s_barrier
	s_setprio 1
	s_waitcnt lgkmcnt(0)
	v_mfma_f32_16x16x32_bf16 v[96:99], v[112:115], v[202:205], v[96:99]
	v_mfma_f32_16x16x32_bf16 v[72:75], v[112:115], v[178:181], v[72:75]
	v_mfma_f32_16x16x32_bf16 v[76:79], v[120:123], v[178:181], v[76:79]
	v_mfma_f32_16x16x32_bf16 v[80:83], v[112:115], v[186:189], v[80:83]
	v_mfma_f32_16x16x32_bf16 v[84:87], v[120:123], v[186:189], v[84:87]
	v_mfma_f32_16x16x32_bf16 v[88:91], v[112:115], v[194:197], v[88:91]
	v_mfma_f32_16x16x32_bf16 v[92:95], v[120:123], v[194:197], v[92:95]
	v_mfma_f32_16x16x32_bf16 v[210:213], v[116:119], v[206:209], v[96:99]
	s_setprio 0
	s_setprio 1
	v_mfma_f32_16x16x32_bf16 v[96:99], v[120:123], v[202:205], v[100:103]
	v_mfma_f32_16x16x32_bf16 v[72:75], v[116:119], v[182:185], v[72:75]
	v_mfma_f32_16x16x32_bf16 v[76:79], v[124:127], v[182:185], v[76:79]
	v_mfma_f32_16x16x32_bf16 v[80:83], v[116:119], v[190:193], v[80:83]
	v_mfma_f32_16x16x32_bf16 v[84:87], v[124:127], v[190:193], v[84:87]
	v_mfma_f32_16x16x32_bf16 v[88:91], v[116:119], v[198:201], v[88:91]
	v_mfma_f32_16x16x32_bf16 v[92:95], v[124:127], v[198:201], v[92:95]
	v_mfma_f32_16x16x32_bf16 v[100:103], v[124:127], v[206:209], v[96:99]
	s_setprio 0
	s_setprio 1
	v_mfma_f32_16x16x32_bf16 v[48:51], v[170:173], v[186:189], v[48:51]
	v_mfma_f32_16x16x32_bf16 v[96:99], v[130:133], v[178:181], v[104:107]
	v_mfma_f32_16x16x32_bf16 v[40:43], v[170:173], v[178:181], v[40:43]
	v_mfma_f32_16x16x32_bf16 v[178:181], v[174:177], v[190:193], v[48:51]
	v_mfma_f32_16x16x32_bf16 v[48:51], v[130:133], v[194:197], v[52:55]
	v_mfma_f32_16x16x32_bf16 v[52:55], v[142:145], v[198:201], v[48:51]
	v_mfma_f32_16x16x32_bf16 v[48:51], v[170:173], v[194:197], v[56:59]
	v_mfma_f32_16x16x32_bf16 v[214:217], v[142:145], v[182:185], v[96:99]
	s_setprio 0
	s_setprio 1
	v_mfma_f32_16x16x32_bf16 v[40:43], v[174:177], v[182:185], v[40:43]
	v_mfma_f32_16x16x32_bf16 v[182:185], v[174:177], v[198:201], v[48:51]
	v_mfma_f32_16x16x32_bf16 v[48:51], v[130:133], v[202:205], v[60:63]
	v_mfma_f32_16x16x32_bf16 v[44:47], v[130:133], v[186:189], v[44:47]
	v_mfma_f32_16x16x32_bf16 v[60:63], v[142:145], v[206:209], v[48:51]
	v_mfma_f32_16x16x32_bf16 v[48:51], v[170:173], v[202:205], v[64:67]
	v_mfma_f32_16x16x32_bf16 v[44:47], v[142:145], v[190:193], v[44:47]
	v_mfma_f32_16x16x32_bf16 v[64:67], v[174:177], v[206:209], v[48:51]
	s_setprio 0
	s_barrier
	s_mov_b32 m0, s49
	s_nop 2
	ds_read_b128 v[48:51], v137 offset:16384
	ds_read_b128 v[56:59], v137 offset:17408
	ds_read_b128 v[96:99], v137 offset:18432
	ds_read_b128 v[104:107], v137 offset:19456
	ds_read_b128 v[186:189], v137 offset:20480
	ds_read_b128 v[190:193], v137 offset:21504
	ds_read_b128 v[194:197], v137 offset:22528
	ds_read_b128 v[198:201], v137 offset:23552
	global_load_lds_dwordx4 v0, s[18:19]
	s_mov_b32 m0, s47
	v_lshl_add_u64 v[134:135], s[18:19], 0, v[0:1]
	global_load_lds_dwordx4 v2, s[18:19]
	s_mov_b32 m0, s48
	v_lshl_add_u64 v[246:247], s[18:19], 0, v[2:3]
	global_load_lds_dwordx4 v0, s[16:17]
	s_mov_b32 m0, s46
	v_lshl_add_u64 v[248:249], s[14:15], 0, v[4:5]
	global_load_lds_dwordx4 v2, s[16:17]
	s_mov_b32 m0, s40
	v_lshl_add_u64 v[250:251], s[14:15], 0, v[6:7]
	global_load_lds_dwordx4 v4, s[14:15]
	s_mov_b32 m0, s45
	s_nop 0
	global_load_lds_dwordx4 v6, s[14:15]
	s_waitcnt vmcnt(8)
	s_waitcnt lgkmcnt(0)
	s_barrier
	s_setprio 1
	s_waitcnt lgkmcnt(0)
	v_mfma_f32_16x16x32_bf16 v[8:11], v[112:115], v[194:197], v[8:11]
	v_mfma_f32_16x16x32_bf16 v[146:149], v[112:115], v[48:51], v[146:149]
	v_mfma_f32_16x16x32_bf16 v[150:153], v[120:123], v[48:51], v[150:153]
	v_mfma_f32_16x16x32_bf16 v[154:157], v[112:115], v[96:99], v[154:157]
	v_mfma_f32_16x16x32_bf16 v[158:161], v[120:123], v[96:99], v[158:161]
	v_mfma_f32_16x16x32_bf16 v[162:165], v[112:115], v[186:189], v[162:165]
	v_mfma_f32_16x16x32_bf16 v[166:169], v[120:123], v[186:189], v[166:169]
	v_mfma_f32_16x16x32_bf16 v[8:11], v[116:119], v[198:201], v[8:11]
	s_setprio 0
	s_setprio 1
	v_mfma_f32_16x16x32_bf16 v[12:15], v[120:123], v[194:197], v[12:15]
	v_mfma_f32_16x16x32_bf16 v[146:149], v[116:119], v[56:59], v[146:149]
	v_mfma_f32_16x16x32_bf16 v[150:153], v[124:127], v[56:59], v[150:153]
	v_mfma_f32_16x16x32_bf16 v[154:157], v[116:119], v[104:107], v[154:157]
	v_mfma_f32_16x16x32_bf16 v[158:161], v[124:127], v[104:107], v[158:161]
	v_mfma_f32_16x16x32_bf16 v[162:165], v[116:119], v[190:193], v[162:165]
	v_mfma_f32_16x16x32_bf16 v[166:169], v[124:127], v[190:193], v[166:169]
	v_mfma_f32_16x16x32_bf16 v[202:205], v[124:127], v[198:201], v[12:15]
	s_setprio 0
	s_setprio 1
	v_mfma_f32_16x16x32_bf16 v[12:15], v[130:133], v[48:51], v[16:19]
	v_mfma_f32_16x16x32_bf16 v[16:19], v[142:145], v[56:59], v[12:15]
	v_mfma_f32_16x16x32_bf16 v[12:15], v[170:173], v[48:51], v[20:23]
	v_mfma_f32_16x16x32_bf16 v[206:209], v[174:177], v[56:59], v[12:15]
	v_mfma_f32_16x16x32_bf16 v[12:15], v[130:133], v[96:99], v[32:35]
	v_mfma_f32_16x16x32_bf16 v[32:35], v[142:145], v[104:107], v[12:15]
	v_mfma_f32_16x16x32_bf16 v[12:15], v[170:173], v[96:99], v[36:39]
	v_mfma_f32_16x16x32_bf16 v[218:221], v[174:177], v[104:107], v[12:15]
	s_setprio 0
	s_setprio 1
	v_mfma_f32_16x16x32_bf16 v[12:15], v[130:133], v[186:189], v[68:71]
	v_mfma_f32_16x16x32_bf16 v[222:225], v[142:145], v[190:193], v[12:15]
	v_mfma_f32_16x16x32_bf16 v[12:15], v[170:173], v[186:189], v[108:111]
	v_mfma_f32_16x16x32_bf16 v[186:189], v[174:177], v[190:193], v[12:15]
	v_mfma_f32_16x16x32_bf16 v[12:15], v[130:133], v[194:197], v[24:27]
	v_mfma_f32_16x16x32_bf16 v[130:133], v[142:145], v[198:201], v[12:15]
	v_mfma_f32_16x16x32_bf16 v[12:15], v[170:173], v[194:197], v[28:31]
	v_mfma_f32_16x16x32_bf16 v[140:143], v[174:177], v[198:201], v[12:15]
	s_setprio 0
	s_barrier
	s_nop 4
	ds_read_b128 v[12:15], v139
	ds_read_b128 v[24:27], v139 offset:1024
	ds_read_b128 v[170:173], v139 offset:2048
	ds_read_b128 v[174:177], v139 offset:3072
	ds_read_b128 v[190:193], v138
	ds_read_b128 v[194:197], v138 offset:1024
	ds_read_b128 v[198:201], v138 offset:2048
	ds_read_b128 v[226:229], v138 offset:3072
	s_mov_b32 m0, s34
	ds_read_b128 v[20:23], v137 offset:32768
	ds_read_b128 v[28:31], v137 offset:33792
	ds_read_b128 v[36:39], v137 offset:34816
	ds_read_b128 v[68:71], v137 offset:35840
	ds_read_b128 v[230:233], v137 offset:36864
	ds_read_b128 v[234:237], v137 offset:37888
	ds_read_b128 v[238:241], v137 offset:38912
	ds_read_b128 v[242:245], v137 offset:39936
	global_load_lds_dwordx4 v4, s[20:21]
	s_mov_b32 m0, s35
	s_nop 0
	global_load_lds_dwordx4 v6, s[20:21]
	s_waitcnt vmcnt(8)
	s_waitcnt lgkmcnt(0)
	s_barrier
; #define PG8_BAR __builtin_amdgcn_s_barrier()
; template <int ROT, class Epi0, class Epi1, class Late, class Post0>
; __device__ __forceinline__ void gemm_phase_pair(PG8_LAS unsigned char* lds, const Gemm g0, const Gemm g1, const Unit u, const Epi0& E0, const Epi1& E1, int wid_in, const Late& late, const Post0& post0) {
;     ...
;     if (wr == 0) PG8_BAR;
	s_setprio 1
	s_waitcnt lgkmcnt(0)
	v_mfma_f32_16x16x32_bf16 v[4:7], v[12:15], v[20:23], v[72:75]
	v_mfma_f32_16x16x32_bf16 v[120:123], v[24:27], v[28:31], v[4:7]
	v_mfma_f32_16x16x32_bf16 v[4:7], v[170:173], v[20:23], v[76:79]
	v_mfma_f32_16x16x32_bf16 v[112:115], v[174:177], v[28:31], v[4:7]
	v_mfma_f32_16x16x32_bf16 v[4:7], v[12:15], v[36:39], v[80:83]
	v_mfma_f32_16x16x32_bf16 v[104:107], v[24:27], v[68:71], v[4:7]
	v_mfma_f32_16x16x32_bf16 v[4:7], v[170:173], v[36:39], v[84:87]
	v_mfma_f32_16x16x32_bf16 v[96:99], v[174:177], v[68:71], v[4:7]
	s_setprio 0
	s_setprio 1
	v_mfma_f32_16x16x32_bf16 v[4:7], v[12:15], v[230:233], v[88:91]
	v_mfma_f32_16x16x32_bf16 v[88:91], v[24:27], v[234:237], v[4:7]
	v_mfma_f32_16x16x32_bf16 v[4:7], v[170:173], v[230:233], v[92:95]
	v_mfma_f32_16x16x32_bf16 v[80:83], v[174:177], v[234:237], v[4:7]
	v_mfma_f32_16x16x32_bf16 v[4:7], v[12:15], v[238:241], v[210:213]
	v_mfma_f32_16x16x32_bf16 v[56:59], v[24:27], v[242:245], v[4:7]
	v_mfma_f32_16x16x32_bf16 v[4:7], v[170:173], v[238:241], v[100:103]
	v_mfma_f32_16x16x32_bf16 v[48:51], v[174:177], v[242:245], v[4:7]
	s_setprio 0
	s_setprio 1
	v_mfma_f32_16x16x32_bf16 v[4:7], v[190:193], v[20:23], v[214:217]
	v_mfma_f32_16x16x32_bf16 v[124:127], v[194:197], v[28:31], v[4:7]
	v_mfma_f32_16x16x32_bf16 v[4:7], v[198:201], v[20:23], v[40:43]
	v_mfma_f32_16x16x32_bf16 v[116:119], v[226:229], v[28:31], v[4:7]
	v_mfma_f32_16x16x32_bf16 v[4:7], v[190:193], v[36:39], v[44:47]
	v_mfma_f32_16x16x32_bf16 v[108:111], v[194:197], v[68:71], v[4:7]
	v_mfma_f32_16x16x32_bf16 v[4:7], v[198:201], v[36:39], v[178:181]
	v_mfma_f32_16x16x32_bf16 v[100:103], v[226:229], v[68:71], v[4:7]
	s_setprio 0
	s_setprio 1
	v_mfma_f32_16x16x32_bf16 v[4:7], v[190:193], v[230:233], v[52:55]
	v_mfma_f32_16x16x32_bf16 v[92:95], v[194:197], v[234:237], v[4:7]
	v_mfma_f32_16x16x32_bf16 v[4:7], v[198:201], v[230:233], v[182:185]
	v_mfma_f32_16x16x32_bf16 v[84:87], v[226:229], v[234:237], v[4:7]
	v_mfma_f32_16x16x32_bf16 v[4:7], v[190:193], v[238:241], v[60:63]
	v_mfma_f32_16x16x32_bf16 v[60:63], v[194:197], v[242:245], v[4:7]
	v_mfma_f32_16x16x32_bf16 v[4:7], v[198:201], v[238:241], v[64:67]
	v_mfma_f32_16x16x32_bf16 v[52:55], v[226:229], v[242:245], v[4:7]
	s_setprio 0
	s_barrier
	s_mov_b64 s[0:1], 0x80
	s_mov_b32 m0, s44
	s_nop 2
	v_lshl_add_u64 v[4:5], v[134:135], 0, s[0:1]
	ds_read_b128 v[40:43], v137 offset:49152
	ds_read_b128 v[64:67], v137 offset:50176
	ds_read_b128 v[178:181], v137 offset:51200
	ds_read_b128 v[182:185], v137 offset:52224
	ds_read_b128 v[210:213], v137 offset:53248
	ds_read_b128 v[214:217], v137 offset:54272
	ds_read_b128 v[230:233], v137 offset:55296
	ds_read_b128 v[234:237], v137 offset:56320
	global_load_lds_dwordx4 v[4:5], off
	v_lshl_add_u64 v[4:5], v[246:247], 0, s[0:1]
	s_mov_b32 m0, s42
	s_nop 0
	global_load_lds_dwordx4 v[4:5], off
	s_mov_b32 m0, s43
	s_nop 0
	global_load_lds_dwordx4 v0, s[22:23]
	s_mov_b32 m0, s41
	v_lshl_add_u64 v[0:1], v[248:249], 0, s[0:1]
	global_load_lds_dwordx4 v2, s[22:23]
	s_mov_b32 m0, s13
	s_nop 0
	global_load_lds_dwordx4 v[0:1], off
	v_lshl_add_u64 v[0:1], v[250:251], 0, s[0:1]
	s_mov_b32 m0, s33
	s_nop 0
	global_load_lds_dwordx4 v[0:1], off
	s_waitcnt vmcnt(8)
	s_waitcnt lgkmcnt(0)
	s_barrier
	s_setprio 1
	s_waitcnt lgkmcnt(0)
	v_mfma_f32_16x16x32_bf16 v[0:3], v[12:15], v[40:43], v[146:149]
	v_mfma_f32_16x16x32_bf16 v[76:79], v[24:27], v[64:67], v[0:3]
	v_mfma_f32_16x16x32_bf16 v[0:3], v[170:173], v[40:43], v[150:153]
	v_mfma_f32_16x16x32_bf16 v[68:71], v[174:177], v[64:67], v[0:3]
	v_mfma_f32_16x16x32_bf16 v[0:3], v[12:15], v[178:181], v[154:157]
	v_mfma_f32_16x16x32_bf16 v[44:47], v[24:27], v[182:185], v[0:3]
	v_mfma_f32_16x16x32_bf16 v[0:3], v[170:173], v[178:181], v[158:161]
	v_mfma_f32_16x16x32_bf16 v[36:39], v[174:177], v[182:185], v[0:3]
	s_setprio 0
	s_setprio 1
	v_mfma_f32_16x16x32_bf16 v[0:3], v[12:15], v[210:213], v[162:165]
	v_mfma_f32_16x16x32_bf16 v[28:31], v[24:27], v[214:217], v[0:3]
	v_mfma_f32_16x16x32_bf16 v[0:3], v[170:173], v[210:213], v[166:169]
	v_mfma_f32_16x16x32_bf16 v[20:23], v[174:177], v[214:217], v[0:3]
	v_mfma_f32_16x16x32_bf16 v[0:3], v[12:15], v[230:233], v[8:11]
	v_mfma_f32_16x16x32_bf16 v[12:15], v[24:27], v[234:237], v[0:3]
	v_mfma_f32_16x16x32_bf16 v[0:3], v[170:173], v[230:233], v[202:205]
	v_mfma_f32_16x16x32_bf16 v[4:7], v[174:177], v[234:237], v[0:3]
	s_setprio 0
	s_setprio 1
	v_mfma_f32_16x16x32_bf16 v[0:3], v[190:193], v[40:43], v[16:19]
	v_mfma_f32_16x16x32_bf16 v[72:75], v[194:197], v[64:67], v[0:3]
	v_mfma_f32_16x16x32_bf16 v[0:3], v[198:201], v[40:43], v[206:209]
	v_mfma_f32_16x16x32_bf16 v[64:67], v[226:229], v[64:67], v[0:3]
	v_mfma_f32_16x16x32_bf16 v[0:3], v[190:193], v[178:181], v[32:35]
	v_mfma_f32_16x16x32_bf16 v[40:43], v[194:197], v[182:185], v[0:3]
	v_mfma_f32_16x16x32_bf16 v[0:3], v[198:201], v[178:181], v[218:221]
	v_mfma_f32_16x16x32_bf16 v[32:35], v[226:229], v[182:185], v[0:3]
	s_setprio 0
	s_setprio 1
	v_mfma_f32_16x16x32_bf16 v[0:3], v[190:193], v[210:213], v[222:225]
	v_mfma_f32_16x16x32_bf16 v[24:27], v[194:197], v[214:217], v[0:3]
	v_mfma_f32_16x16x32_bf16 v[0:3], v[198:201], v[210:213], v[186:189]
	v_mfma_f32_16x16x32_bf16 v[16:19], v[226:229], v[214:217], v[0:3]
	v_mfma_f32_16x16x32_bf16 v[0:3], v[190:193], v[230:233], v[130:133]
	v_mfma_f32_16x16x32_bf16 v[8:11], v[194:197], v[234:237], v[0:3]
	v_mfma_f32_16x16x32_bf16 v[0:3], v[198:201], v[230:233], v[140:143]
	v_mfma_f32_16x16x32_bf16 v[0:3], v[226:229], v[234:237], v[0:3]
	s_setprio 0
	s_barrier
	s_andn2_b64 vcc, exec, s[4:5]
	s_cbranch_vccnz .LBB0_888
	s_barrier

; #define PG8_STAGE(bufoff, gbase, voff) do { _Pragma("unroll") for (int _i = 0; _i < 2; ++_i) \
;         __builtin_amdgcn_global_load_lds((const unsigned*)((const char*)(gbase) + (voff)[_i]), (PG8_LAS unsigned*)(lds + (bufoff) + ldsw + _i * 8192), 16, 0, 0); } while (0)
; #define PG8_LDA(dst, b, h) do { _Pragma("unroll") for (int m = 0; m < 4; ++m) _Pragma("unroll") for (int k = 0; k < 2; ++k) dst[m][k] = *(const PG8_LAS bf16x8*)(lds + PG8_SA(b, h) + aoff + m * 2048 + k * 1024); } while (0)
; #define PG8_LDB(dst, b, h) do { _Pragma("unroll") for (int n = 0; n < 2; ++n) _Pragma("unroll") for (int k = 0; k < 2; ++k) dst[n][k] = *(const PG8_LAS bf16x8*)(lds + PG8_SB(b, h) + boff + n * 2048 + k * 1024); } while (0)
; #define PG8_MMA(ai, bj, At, Bt) do { __builtin_amdgcn_s_setprio(1); _Pragma("unroll") for (int m = 0; m < 4; ++m) _Pragma("unroll") for (int n = 0; n < 2; ++n) _Pragma("unroll") for (int k = 0; k < 2; ++k) \
;         acc[ai][bj][m][n] = __builtin_amdgcn_mfma_f32_16x16x32_bf16(Bt[n][k], At[m][k], acc[ai][bj][m][n], 0, 0, 0); __builtin_amdgcn_s_setprio(0); } while (0)
; #define PG8_WAIT_V(n) asm volatile("s_waitcnt vmcnt(" #n ")" ::: "memory")
; #define PG8_WAIT_L(n) asm volatile("s_waitcnt lgkmcnt(" #n ")" ::: "memory")
; #define PG8_BAR __builtin_amdgcn_s_barrier()
; #define PG8_SCHED __builtin_amdgcn_sched_barrier(0)
; template <class Epi, class Sched, bool ALIGN_EPI = false, bool SP2 = false>
; __device__ __forceinline__ void gemm_phase(PG8_LAS unsigned char* lds, const Gemm g, const Sched& S, const Epi& E, int wid_in) {
;     ...
;             PG8_LDB(B0, 0, 0); PG8_LDB(B1, 0, 1); PG8_SCHED; PG8_LDA(At, 0, 0); PG8_STAGE(PG8_SA(1, 1), a1 + hstep, voffA);
;             PG8_WAIT_V(8); PG8_WAIT_L(0); PG8_BAR; PG8_MMA(0, 0, At, B0); PG8_MMA(0, 1, At, B1); PG8_BAR; PG8_SCHED;
;             PG8_LDA(At, 0, 1); PG8_STAGE(PG8_SB(0, 0), b2, voffB); PG8_STAGE(PG8_SB(0, 1), b2 + hstep, voffB); PG8_STAGE(PG8_SA(0, 0), a2, voffA);
.LBB0_986:
	v_add_u32_e32 v155, s43, v153
	ds_read_b128 v[156:159], v155
	ds_read_b128 v[160:163], v155 offset:1024
	ds_read_b128 v[164:167], v155 offset:2048
	ds_read_b128 v[168:171], v155 offset:3072
	v_add_u32_e32 v155, s44, v153
	s_add_u32 s28, s10, s26
	ds_read_b128 v[172:175], v155
	ds_read_b128 v[176:179], v155 offset:1024
	ds_read_b128 v[180:183], v155 offset:2048
	ds_read_b128 v[184:187], v155 offset:3072
	s_addc_u32 s29, s11, s27
	s_add_u32 s28, s28, 0x100
	s_addc_u32 s29, s29, 0
	s_add_u32 s49, s23, s26
	s_addc_u32 s50, s45, s27
	s_cmpk_eq_i32 s26, 0x700
	s_cselect_b32 s31, s19, s29
	s_cselect_b32 s30, s46, s28
	s_cselect_b32 s29, s17, s50
	s_cselect_b32 s28, s47, s49
	v_lshl_add_u64 v[220:221], v[144:145], 0, s[26:27]
	s_add_i32 m0, s36, 0xc000
	ds_read_b128 v[188:191], v154
	ds_read_b128 v[192:195], v154 offset:1024
	ds_read_b128 v[196:199], v154 offset:2048
	ds_read_b128 v[200:203], v154 offset:3072
	ds_read_b128 v[204:207], v154 offset:4096
	ds_read_b128 v[208:211], v154 offset:5120
	ds_read_b128 v[212:215], v154 offset:6144
	ds_read_b128 v[216:219], v154 offset:7168
	global_load_lds_dwordx4 v[220:221], off
	v_lshl_add_u64 v[220:221], v[146:147], 0, s[26:27]
	s_add_i32 m0, s36, 0xe000
	s_nop 0
	global_load_lds_dwordx4 v[220:221], off
	s_waitcnt vmcnt(8)
	s_waitcnt lgkmcnt(0)
	s_barrier
	s_setprio 1
	s_waitcnt lgkmcnt(0)
	v_mfma_f32_16x16x32_bf16 v[60:63], v[156:159], v[188:191], v[60:63]
	v_mfma_f32_16x16x32_bf16 v[56:59], v[164:167], v[188:191], v[56:59]
	v_mfma_f32_16x16x32_bf16 v[88:91], v[156:159], v[196:199], v[88:91]
	v_mfma_f32_16x16x32_bf16 v[84:87], v[164:167], v[196:199], v[84:87]
	v_mfma_f32_16x16x32_bf16 v[108:111], v[156:159], v[204:207], v[108:111]
	v_mfma_f32_16x16x32_bf16 v[104:107], v[164:167], v[204:207], v[104:107]
	v_mfma_f32_16x16x32_bf16 v[124:127], v[156:159], v[212:215], v[124:127]
	v_mfma_f32_16x16x32_bf16 v[120:123], v[164:167], v[212:215], v[120:123]
	s_setprio 0
	s_setprio 1
	v_mfma_f32_16x16x32_bf16 v[60:63], v[160:163], v[192:195], v[60:63]
	v_mfma_f32_16x16x32_bf16 v[56:59], v[168:171], v[192:195], v[56:59]
	v_mfma_f32_16x16x32_bf16 v[88:91], v[160:163], v[200:203], v[88:91]
	v_mfma_f32_16x16x32_bf16 v[84:87], v[168:171], v[200:203], v[84:87]
	v_mfma_f32_16x16x32_bf16 v[108:111], v[160:163], v[208:211], v[108:111]
	v_mfma_f32_16x16x32_bf16 v[104:107], v[168:171], v[208:211], v[104:107]
	v_mfma_f32_16x16x32_bf16 v[124:127], v[160:163], v[216:219], v[124:127]
	v_mfma_f32_16x16x32_bf16 v[120:123], v[168:171], v[216:219], v[120:123]
	s_setprio 0
	s_setprio 1
	v_mfma_f32_16x16x32_bf16 v[36:39], v[172:175], v[188:191], v[36:39]
	v_mfma_f32_16x16x32_bf16 v[32:35], v[180:183], v[188:191], v[32:35]
	v_mfma_f32_16x16x32_bf16 v[68:71], v[172:175], v[196:199], v[68:71]
	v_mfma_f32_16x16x32_bf16 v[64:67], v[180:183], v[196:199], v[64:67]
	v_mfma_f32_16x16x32_bf16 v[100:103], v[172:175], v[204:207], v[100:103]
	v_mfma_f32_16x16x32_bf16 v[96:99], v[180:183], v[204:207], v[96:99]
	v_mfma_f32_16x16x32_bf16 v[116:119], v[172:175], v[212:215], v[116:119]
	v_mfma_f32_16x16x32_bf16 v[112:115], v[180:183], v[212:215], v[112:115]
	s_setprio 0
	s_setprio 1
	v_mfma_f32_16x16x32_bf16 v[36:39], v[176:179], v[192:195], v[36:39]
	v_mfma_f32_16x16x32_bf16 v[32:35], v[184:187], v[192:195], v[32:35]
	v_mfma_f32_16x16x32_bf16 v[68:71], v[176:179], v[200:203], v[68:71]
	v_mfma_f32_16x16x32_bf16 v[64:67], v[184:187], v[200:203], v[64:67]
	v_mfma_f32_16x16x32_bf16 v[100:103], v[176:179], v[208:211], v[100:103]
	v_mfma_f32_16x16x32_bf16 v[96:99], v[184:187], v[208:211], v[96:99]
	v_mfma_f32_16x16x32_bf16 v[116:119], v[176:179], v[216:219], v[116:119]
	v_mfma_f32_16x16x32_bf16 v[112:115], v[184:187], v[216:219], v[112:115]
	s_setprio 0
	s_barrier
	s_add_i32 s49, s43, s35
	v_lshl_add_u64 v[220:221], s[28:29], 0, v[130:131]
	s_mov_b32 m0, s49
	ds_read_b128 v[188:191], v154 offset:16384
	ds_read_b128 v[192:195], v154 offset:17408
	ds_read_b128 v[196:199], v154 offset:18432
	ds_read_b128 v[200:203], v154 offset:19456
	ds_read_b128 v[204:207], v154 offset:20480
	ds_read_b128 v[208:211], v154 offset:21504
	ds_read_b128 v[212:215], v154 offset:22528
	ds_read_b128 v[216:219], v154 offset:23552
	global_load_lds_dwordx4 v[220:221], off
	s_add_i32 m0, s49, 0x2000
	s_add_u32 s50, s28, 0x40000
	v_lshl_add_u64 v[222:223], s[28:29], 0, v[134:135]
	s_addc_u32 s51, s29, 0
	s_add_i32 s49, s44, s35
	global_load_lds_dwordx4 v[222:223], off
	v_lshl_add_u64 v[224:225], s[50:51], 0, v[130:131]
	s_mov_b32 m0, s49
	v_lshl_add_u64 v[226:227], s[30:31], 0, v[132:133]
	global_load_lds_dwordx4 v[224:225], off
	v_lshl_add_u64 v[224:225], s[50:51], 0, v[134:135]
	s_add_i32 m0, s49, 0x2000
	s_nop 0
	global_load_lds_dwordx4 v[224:225], off
	v_lshl_add_u64 v[224:225], s[30:31], 0, v[128:129]
	s_mov_b32 m0, s36
	s_nop 0
	global_load_lds_dwordx4 v[224:225], off
	s_mov_b32 m0, s37
	s_nop 0
	global_load_lds_dwordx4 v[226:227], off
	s_waitcnt vmcnt(8)
	s_waitcnt lgkmcnt(0)
	s_barrier
; #define PG8_STAGE(bufoff, gbase, voff) do { _Pragma("unroll") for (int _i = 0; _i < 2; ++_i) \
;         __builtin_amdgcn_global_load_lds((const unsigned*)((const char*)(gbase) + (voff)[_i]), (PG8_LAS unsigned*)(lds + (bufoff) + ldsw + _i * 8192), 16, 0, 0); } while (0)
; #define PG8_LDA(dst, b, h) do { _Pragma("unroll") for (int m = 0; m < 4; ++m) _Pragma("unroll") for (int k = 0; k < 2; ++k) dst[m][k] = *(const PG8_LAS bf16x8*)(lds + PG8_SA(b, h) + aoff + m * 2048 + k * 1024); } while (0)
; #define PG8_LDB(dst, b, h) do { _Pragma("unroll") for (int n = 0; n < 2; ++n) _Pragma("unroll") for (int k = 0; k < 2; ++k) dst[n][k] = *(const PG8_LAS bf16x8*)(lds + PG8_SB(b, h) + boff + n * 2048 + k * 1024); } while (0)
; #define PG8_MMA(ai, bj, At, Bt) do { __builtin_amdgcn_s_setprio(1); _Pragma("unroll") for (int m = 0; m < 4; ++m) _Pragma("unroll") for (int n = 0; n < 2; ++n) _Pragma("unroll") for (int k = 0; k < 2; ++k) \
;         acc[ai][bj][m][n] = __builtin_amdgcn_mfma_f32_16x16x32_bf16(Bt[n][k], At[m][k], acc[ai][bj][m][n], 0, 0, 0); __builtin_amdgcn_s_setprio(0); } while (0)
; #define PG8_WAIT_V(n) asm volatile("s_waitcnt vmcnt(" #n ")" ::: "memory")
; #define PG8_WAIT_L(n) asm volatile("s_waitcnt lgkmcnt(" #n ")" ::: "memory")
; #define PG8_BAR __builtin_amdgcn_s_barrier()
; #define PG8_SCHED __builtin_amdgcn_sched_barrier(0)
; template <class Epi, class Sched, bool ALIGN_EPI = false, bool SP2 = false>
; __device__ __forceinline__ void gemm_phase(PG8_LAS unsigned char* lds, const Gemm g, const Sched& S, const Epi& E, int wid_in) {
;     ...
;             PG8_WAIT_V(8); PG8_WAIT_L(0); PG8_BAR; PG8_MMA(1, 0, At, B0); PG8_MMA(1, 1, At, B1); PG8_BAR; PG8_SCHED;
;             PG8_LDB(B0, 1, 0); PG8_LDB(B1, 1, 1); PG8_SCHED; PG8_LDA(At, 1, 0); PG8_STAGE(PG8_SA(0, 1), a2 + hstep, voffA);
;             PG8_WAIT_V(8); PG8_WAIT_L(0); PG8_BAR; PG8_MMA(0, 0, At, B0); PG8_MMA(0, 1, At, B1); PG8_BAR; PG8_SCHED;
;             PG8_LDA(At, 1, 1); PG8_STAGE(PG8_SB(1, 0), b3, voffB); PG8_STAGE(PG8_SB(1, 1), b3 + hstep, voffB); PG8_STAGE(PG8_SA(1, 0), a3, voffA);
	s_setprio 1
	s_waitcnt lgkmcnt(0)
	v_mfma_f32_16x16x32_bf16 v[92:95], v[156:159], v[188:191], v[92:95]
	v_mfma_f32_16x16x32_bf16 v[80:83], v[164:167], v[188:191], v[80:83]
	v_mfma_f32_16x16x32_bf16 v[52:55], v[156:159], v[196:199], v[52:55]
	v_mfma_f32_16x16x32_bf16 v[48:51], v[164:167], v[196:199], v[48:51]
	v_mfma_f32_16x16x32_bf16 v[28:31], v[156:159], v[204:207], v[28:31]
	v_mfma_f32_16x16x32_bf16 v[24:27], v[164:167], v[204:207], v[24:27]
	v_mfma_f32_16x16x32_bf16 v[12:15], v[156:159], v[212:215], v[12:15]
	v_mfma_f32_16x16x32_bf16 v[8:11], v[164:167], v[212:215], v[8:11]
	s_setprio 0
	s_setprio 1
	v_mfma_f32_16x16x32_bf16 v[92:95], v[160:163], v[192:195], v[92:95]
	v_mfma_f32_16x16x32_bf16 v[80:83], v[168:171], v[192:195], v[80:83]
	v_mfma_f32_16x16x32_bf16 v[52:55], v[160:163], v[200:203], v[52:55]
	v_mfma_f32_16x16x32_bf16 v[48:51], v[168:171], v[200:203], v[48:51]
	v_mfma_f32_16x16x32_bf16 v[28:31], v[160:163], v[208:211], v[28:31]
	v_mfma_f32_16x16x32_bf16 v[24:27], v[168:171], v[208:211], v[24:27]
	v_mfma_f32_16x16x32_bf16 v[12:15], v[160:163], v[216:219], v[12:15]
	v_mfma_f32_16x16x32_bf16 v[8:11], v[168:171], v[216:219], v[8:11]
	s_setprio 0
	s_setprio 1
	v_mfma_f32_16x16x32_bf16 v[76:79], v[172:175], v[188:191], v[76:79]
	v_mfma_f32_16x16x32_bf16 v[72:75], v[180:183], v[188:191], v[72:75]
	v_mfma_f32_16x16x32_bf16 v[44:47], v[172:175], v[196:199], v[44:47]
	v_mfma_f32_16x16x32_bf16 v[40:43], v[180:183], v[196:199], v[40:43]
	v_mfma_f32_16x16x32_bf16 v[20:23], v[172:175], v[204:207], v[20:23]
	v_mfma_f32_16x16x32_bf16 v[16:19], v[180:183], v[204:207], v[16:19]
	v_mfma_f32_16x16x32_bf16 v[4:7], v[172:175], v[212:215], v[4:7]
	v_mfma_f32_16x16x32_bf16 v[0:3], v[180:183], v[212:215], v[0:3]
	s_setprio 0
	s_setprio 1
	v_mfma_f32_16x16x32_bf16 v[76:79], v[176:179], v[192:195], v[76:79]
	v_mfma_f32_16x16x32_bf16 v[72:75], v[184:187], v[192:195], v[72:75]
	v_mfma_f32_16x16x32_bf16 v[44:47], v[176:179], v[200:203], v[44:47]
	v_mfma_f32_16x16x32_bf16 v[40:43], v[184:187], v[200:203], v[40:43]
	v_mfma_f32_16x16x32_bf16 v[20:23], v[176:179], v[208:211], v[20:23]
	v_mfma_f32_16x16x32_bf16 v[16:19], v[184:187], v[208:211], v[16:19]
	v_mfma_f32_16x16x32_bf16 v[4:7], v[176:179], v[216:219], v[4:7]
	v_mfma_f32_16x16x32_bf16 v[0:3], v[184:187], v[216:219], v[0:3]
	s_setprio 0
	s_barrier
	s_add_i32 s49, 0, 0x18000
	v_add_u32_e32 v155, s49, v153
	s_add_i32 s50, 0, 0x1c000
	ds_read_b128 v[156:159], v155
	ds_read_b128 v[160:163], v155 offset:1024
	ds_read_b128 v[164:167], v155 offset:2048
	ds_read_b128 v[168:171], v155 offset:3072
	v_add_u32_e32 v155, s50, v153
	ds_read_b128 v[172:175], v155
	ds_read_b128 v[176:179], v155 offset:1024
	ds_read_b128 v[180:183], v155 offset:2048
	ds_read_b128 v[184:187], v155 offset:3072
	s_add_u32 s30, s30, 0x40000
	s_addc_u32 s31, s31, 0
	s_mov_b32 m0, s38
	v_lshl_add_u64 v[228:229], s[30:31], 0, v[128:129]
	ds_read_b128 v[188:191], v154 offset:32768
	ds_read_b128 v[192:195], v154 offset:33792
	ds_read_b128 v[196:199], v154 offset:34816
	ds_read_b128 v[200:203], v154 offset:35840
	ds_read_b128 v[204:207], v154 offset:36864
	ds_read_b128 v[208:211], v154 offset:37888
	ds_read_b128 v[212:215], v154 offset:38912
	ds_read_b128 v[216:219], v154 offset:39936
	global_load_lds_dwordx4 v[228:229], off
	v_lshl_add_u64 v[228:229], s[30:31], 0, v[132:133]
	s_mov_b32 m0, s39
	s_nop 0
	global_load_lds_dwordx4 v[228:229], off
	s_waitcnt vmcnt(8)
	s_waitcnt lgkmcnt(0)
	s_barrier
	s_setprio 1
	s_waitcnt lgkmcnt(0)
	v_mfma_f32_16x16x32_bf16 v[60:63], v[156:159], v[188:191], v[60:63]
	v_mfma_f32_16x16x32_bf16 v[56:59], v[164:167], v[188:191], v[56:59]
	v_mfma_f32_16x16x32_bf16 v[88:91], v[156:159], v[196:199], v[88:91]
	v_mfma_f32_16x16x32_bf16 v[84:87], v[164:167], v[196:199], v[84:87]
	v_mfma_f32_16x16x32_bf16 v[108:111], v[156:159], v[204:207], v[108:111]
	v_mfma_f32_16x16x32_bf16 v[104:107], v[164:167], v[204:207], v[104:107]
	v_mfma_f32_16x16x32_bf16 v[124:127], v[156:159], v[212:215], v[124:127]
	v_mfma_f32_16x16x32_bf16 v[120:123], v[164:167], v[212:215], v[120:123]
	s_setprio 0
	s_setprio 1
	v_mfma_f32_16x16x32_bf16 v[60:63], v[160:163], v[192:195], v[60:63]
	v_mfma_f32_16x16x32_bf16 v[56:59], v[168:171], v[192:195], v[56:59]
	v_mfma_f32_16x16x32_bf16 v[88:91], v[160:163], v[200:203], v[88:91]
	v_mfma_f32_16x16x32_bf16 v[84:87], v[168:171], v[200:203], v[84:87]
	v_mfma_f32_16x16x32_bf16 v[108:111], v[160:163], v[208:211], v[108:111]
	v_mfma_f32_16x16x32_bf16 v[104:107], v[168:171], v[208:211], v[104:107]
	v_mfma_f32_16x16x32_bf16 v[124:127], v[160:163], v[216:219], v[124:127]
	v_mfma_f32_16x16x32_bf16 v[120:123], v[168:171], v[216:219], v[120:123]
	s_setprio 0
	s_setprio 1
	v_mfma_f32_16x16x32_bf16 v[36:39], v[172:175], v[188:191], v[36:39]
	v_mfma_f32_16x16x32_bf16 v[32:35], v[180:183], v[188:191], v[32:35]
	v_mfma_f32_16x16x32_bf16 v[68:71], v[172:175], v[196:199], v[68:71]
	v_mfma_f32_16x16x32_bf16 v[64:67], v[180:183], v[196:199], v[64:67]
	v_mfma_f32_16x16x32_bf16 v[100:103], v[172:175], v[204:207], v[100:103]
	v_mfma_f32_16x16x32_bf16 v[96:99], v[180:183], v[204:207], v[96:99]
	v_mfma_f32_16x16x32_bf16 v[116:119], v[172:175], v[212:215], v[116:119]
	v_mfma_f32_16x16x32_bf16 v[112:115], v[180:183], v[212:215], v[112:115]
	s_setprio 0
	s_setprio 1
	v_mfma_f32_16x16x32_bf16 v[36:39], v[176:179], v[192:195], v[36:39]
	v_mfma_f32_16x16x32_bf16 v[32:35], v[184:187], v[192:195], v[32:35]
	v_mfma_f32_16x16x32_bf16 v[68:71], v[176:179], v[200:203], v[68:71]
	v_mfma_f32_16x16x32_bf16 v[64:67], v[184:187], v[200:203], v[64:67]
	v_mfma_f32_16x16x32_bf16 v[100:103], v[176:179], v[208:211], v[100:103]
	v_mfma_f32_16x16x32_bf16 v[96:99], v[184:187], v[208:211], v[96:99]
	v_mfma_f32_16x16x32_bf16 v[116:119], v[176:179], v[216:219], v[116:119]
	v_mfma_f32_16x16x32_bf16 v[112:115], v[184:187], v[216:219], v[112:115]
	s_setprio 0
	s_barrier
; #define PG8_STAGE(bufoff, gbase, voff) do { _Pragma("unroll") for (int _i = 0; _i < 2; ++_i) \
;         __builtin_amdgcn_global_load_lds((const unsigned*)((const char*)(gbase) + (voff)[_i]), (PG8_LAS unsigned*)(lds + (bufoff) + ldsw + _i * 8192), 16, 0, 0); } while (0)
; #define PG8_LDA(dst, b, h) do { _Pragma("unroll") for (int m = 0; m < 4; ++m) _Pragma("unroll") for (int k = 0; k < 2; ++k) dst[m][k] = *(const PG8_LAS bf16x8*)(lds + PG8_SA(b, h) + aoff + m * 2048 + k * 1024); } while (0)
; #define PG8_MMA(ai, bj, At, Bt) do { __builtin_amdgcn_s_setprio(1); _Pragma("unroll") for (int m = 0; m < 4; ++m) _Pragma("unroll") for (int n = 0; n < 2; ++n) _Pragma("unroll") for (int k = 0; k < 2; ++k) \
;         acc[ai][bj][m][n] = __builtin_amdgcn_mfma_f32_16x16x32_bf16(Bt[n][k], At[m][k], acc[ai][bj][m][n], 0, 0, 0); __builtin_amdgcn_s_setprio(0); } while (0)
; #define PG8_WAIT_V(n) asm volatile("s_waitcnt vmcnt(" #n ")" ::: "memory")
; #define PG8_WAIT_L(n) asm volatile("s_waitcnt lgkmcnt(" #n ")" ::: "memory")
; #define PG8_BAR __builtin_amdgcn_s_barrier()
; #define PG8_SCHED __builtin_amdgcn_sched_barrier(0)
; template <class Epi, class Sched, bool ALIGN_EPI = false, bool SP2 = false>
; __device__ __forceinline__ void gemm_phase(PG8_LAS unsigned char* lds, const Gemm g, const Sched& S, const Epi& E, int wid_in) {
;     ...
;             PG8_LDA(At, 1, 1); PG8_STAGE(PG8_SB(1, 0), b3, voffB); PG8_STAGE(PG8_SB(1, 1), b3 + hstep, voffB); PG8_STAGE(PG8_SA(1, 0), a3, voffA);
;             PG8_WAIT_V(8); PG8_WAIT_L(0); PG8_BAR; PG8_MMA(1, 0, At, B0); PG8_MMA(1, 1, At, B1); PG8_BAR; PG8_SCHED;
;     ...
; #pragma unroll
;         for (int a = 0; a < 2; ++a)
; #pragma unroll
;             for (int b = 0; b < 2; ++b)
; #pragma unroll
;                 for (int m = 0; m < 4; ++m)
; #pragma unroll
;                     for (int n = 0; n < 2; ++n) acc[a][b][m][n] = (f32x4){0.f, 0.f, 0.f, 0.f};
	s_add_i32 s30, s49, s35
	v_lshl_add_u64 v[220:221], v[220:221], 0, s[14:15]
	s_mov_b32 m0, s30
	ds_read_b128 v[188:191], v154 offset:49152
	ds_read_b128 v[192:195], v154 offset:50176
	ds_read_b128 v[196:199], v154 offset:51200
	ds_read_b128 v[200:203], v154 offset:52224
	ds_read_b128 v[204:207], v154 offset:53248
	ds_read_b128 v[208:211], v154 offset:54272
	ds_read_b128 v[212:215], v154 offset:55296
	ds_read_b128 v[216:219], v154 offset:56320
	global_load_lds_dwordx4 v[220:221], off
	s_add_i32 m0, s30, 0x2000
	s_add_u32 s28, s28, 0x40080
	v_lshl_add_u64 v[220:221], v[222:223], 0, s[14:15]
	s_addc_u32 s29, s29, 0
	s_add_i32 s30, s50, s35
	global_load_lds_dwordx4 v[220:221], off
	v_lshl_add_u64 v[220:221], s[28:29], 0, v[130:131]
	s_mov_b32 m0, s30
	s_nop 0
	global_load_lds_dwordx4 v[220:221], off
	v_lshl_add_u64 v[220:221], s[28:29], 0, v[134:135]
	s_add_i32 m0, s30, 0x2000
	s_nop 0
	global_load_lds_dwordx4 v[220:221], off
	v_lshl_add_u64 v[220:221], v[224:225], 0, s[14:15]
	s_mov_b32 m0, s41
	s_nop 0
	global_load_lds_dwordx4 v[220:221], off
	v_lshl_add_u64 v[220:221], v[226:227], 0, s[14:15]
	s_mov_b32 m0, s42
	s_nop 0
	global_load_lds_dwordx4 v[220:221], off
	s_waitcnt vmcnt(8)
	s_waitcnt lgkmcnt(0)
	s_barrier
	s_setprio 1
	s_waitcnt lgkmcnt(0)
	v_mfma_f32_16x16x32_bf16 v[92:95], v[156:159], v[188:191], v[92:95]
	v_mfma_f32_16x16x32_bf16 v[80:83], v[164:167], v[188:191], v[80:83]
	v_mfma_f32_16x16x32_bf16 v[52:55], v[156:159], v[196:199], v[52:55]
	v_mfma_f32_16x16x32_bf16 v[48:51], v[164:167], v[196:199], v[48:51]
	v_mfma_f32_16x16x32_bf16 v[28:31], v[156:159], v[204:207], v[28:31]
	v_mfma_f32_16x16x32_bf16 v[24:27], v[164:167], v[204:207], v[24:27]
	v_mfma_f32_16x16x32_bf16 v[12:15], v[156:159], v[212:215], v[12:15]
	v_mfma_f32_16x16x32_bf16 v[8:11], v[164:167], v[212:215], v[8:11]
	s_setprio 0
	s_setprio 1
	v_mfma_f32_16x16x32_bf16 v[92:95], v[160:163], v[192:195], v[92:95]
	v_mfma_f32_16x16x32_bf16 v[80:83], v[168:171], v[192:195], v[80:83]
	v_mfma_f32_16x16x32_bf16 v[52:55], v[160:163], v[200:203], v[52:55]
	v_mfma_f32_16x16x32_bf16 v[48:51], v[168:171], v[200:203], v[48:51]
	v_mfma_f32_16x16x32_bf16 v[28:31], v[160:163], v[208:211], v[28:31]
	v_mfma_f32_16x16x32_bf16 v[24:27], v[168:171], v[208:211], v[24:27]
	v_mfma_f32_16x16x32_bf16 v[12:15], v[160:163], v[216:219], v[12:15]
	v_mfma_f32_16x16x32_bf16 v[8:11], v[168:171], v[216:219], v[8:11]
	s_setprio 0
	s_setprio 1
	v_mfma_f32_16x16x32_bf16 v[76:79], v[172:175], v[188:191], v[76:79]
	v_mfma_f32_16x16x32_bf16 v[72:75], v[180:183], v[188:191], v[72:75]
	v_mfma_f32_16x16x32_bf16 v[44:47], v[172:175], v[196:199], v[44:47]
	v_mfma_f32_16x16x32_bf16 v[40:43], v[180:183], v[196:199], v[40:43]
	v_mfma_f32_16x16x32_bf16 v[20:23], v[172:175], v[204:207], v[20:23]
	v_mfma_f32_16x16x32_bf16 v[16:19], v[180:183], v[204:207], v[16:19]
	v_mfma_f32_16x16x32_bf16 v[4:7], v[172:175], v[212:215], v[4:7]
	v_mfma_f32_16x16x32_bf16 v[0:3], v[180:183], v[212:215], v[0:3]
	s_setprio 0
	s_setprio 1
	v_mfma_f32_16x16x32_bf16 v[76:79], v[176:179], v[192:195], v[76:79]
	v_mfma_f32_16x16x32_bf16 v[72:75], v[184:187], v[192:195], v[72:75]
	v_mfma_f32_16x16x32_bf16 v[44:47], v[176:179], v[200:203], v[44:47]
	v_mfma_f32_16x16x32_bf16 v[40:43], v[184:187], v[200:203], v[40:43]
	v_mfma_f32_16x16x32_bf16 v[20:23], v[176:179], v[208:211], v[20:23]
	v_mfma_f32_16x16x32_bf16 v[16:19], v[184:187], v[208:211], v[16:19]
	v_mfma_f32_16x16x32_bf16 v[4:7], v[176:179], v[216:219], v[4:7]
	v_mfma_f32_16x16x32_bf16 v[0:3], v[184:187], v[216:219], v[0:3]
	s_setprio 0
	s_barrier
	s_add_i32 s48, s48, 2
	s_add_u32 s26, s26, 0x100
	s_addc_u32 s27, s27, 0
	s_cmp_gt_u32 s48, 13
	s_cbranch_scc0 .LBB0_986
	s_add_u32 s26, s23, 0xffffff00
	s_addc_u32 s27, s45, -1
	s_andn2_b64 vcc, exec, s[2:3]
	s_cbranch_vccnz .LBB0_977
	v_mov_b32_e32 v0, 0
	s_mov_b32 s6, s16
	s_mov_b32 s4, s18
	s_mov_b64 s[10:11], s[24:25]
	s_mov_b32 s40, s22
	v_mov_b32_e32 v1, v0
	v_mov_b32_e32 v2, v0
	v_mov_b32_e32 v3, v0
	v_mov_b32_e32 v4, v0
	v_mov_b32_e32 v5, v0
	v_mov_b32_e32 v6, v0
	v_mov_b32_e32 v7, v0
	v_mov_b32_e32 v16, v0
	v_mov_b32_e32 v17, v0
	v_mov_b32_e32 v18, v0
	v_mov_b32_e32 v19, v0
	v_mov_b32_e32 v20, v0
	v_mov_b32_e32 v21, v0
	v_mov_b32_e32 v22, v0
	v_mov_b32_e32 v23, v0
	v_mov_b32_e32 v40, v0
	v_mov_b32_e32 v41, v0
	v_mov_b32_e32 v42, v0
	v_mov_b32_e32 v43, v0
	v_mov_b32_e32 v44, v0
	v_mov_b32_e32 v45, v0
	v_mov_b32_e32 v46, v0
	v_mov_b32_e32 v47, v0
	v_mov_b32_e32 v72, v0
	v_mov_b32_e32 v73, v0
	v_mov_b32_e32 v74, v0
	v_mov_b32_e32 v75, v0
	v_mov_b32_e32 v76, v0
	v_mov_b32_e32 v77, v0
	v_mov_b32_e32 v78, v0
	v_mov_b32_e32 v79, v0
	v_mov_b32_e32 v8, v0
	v_mov_b32_e32 v9, v0
	v_mov_b32_e32 v10, v0
	v_mov_b32_e32 v11, v0
	v_mov_b32_e32 v12, v0
	v_mov_b32_e32 v13, v0
	v_mov_b32_e32 v14, v0
	v_mov_b32_e32 v15, v0
	v_mov_b32_e32 v24, v0
	v_mov_b32_e32 v25, v0
	v_mov_b32_e32 v26, v0
	v_mov_b32_e32 v27, v0
	v_mov_b32_e32 v28, v0
	v_mov_b32_e32 v29, v0
	v_mov_b32_e32 v30, v0
	v_mov_b32_e32 v31, v0
	v_mov_b32_e32 v48, v0
	v_mov_b32_e32 v49, v0
	v_mov_b32_e32 v50, v0
	v_mov_b32_e32 v51, v0
	v_mov_b32_e32 v52, v0
	v_mov_b32_e32 v53, v0
	v_mov_b32_e32 v54, v0
	v_mov_b32_e32 v55, v0
	v_mov_b32_e32 v80, v0
	v_mov_b32_e32 v81, v0
	v_mov_b32_e32 v82, v0
	v_mov_b32_e32 v83, v0
	v_mov_b32_e32 v92, v0
	v_mov_b32_e32 v93, v0
	v_mov_b32_e32 v94, v0
	v_mov_b32_e32 v95, v0
	v_mov_b32_e32 v112, v0
	v_mov_b32_e32 v113, v0
	v_mov_b32_e32 v114, v0
	v_mov_b32_e32 v115, v0
	v_mov_b32_e32 v116, v0
	v_mov_b32_e32 v117, v0
	v_mov_b32_e32 v118, v0
	v_mov_b32_e32 v119, v0
	v_mov_b32_e32 v96, v0
	v_mov_b32_e32 v97, v0
	v_mov_b32_e32 v98, v0
	v_mov_b32_e32 v99, v0
	v_mov_b32_e32 v100, v0
	v_mov_b32_e32 v101, v0
	v_mov_b32_e32 v102, v0
	v_mov_b32_e32 v103, v0
	v_mov_b32_e32 v64, v0
	v_mov_b32_e32 v65, v0
	v_mov_b32_e32 v66, v0
	v_mov_b32_e32 v67, v0
	v_mov_b32_e32 v68, v0
	v_mov_b32_e32 v69, v0
	v_mov_b32_e32 v70, v0
	v_mov_b32_e32 v71, v0
	v_mov_b32_e32 v32, v0
	v_mov_b32_e32 v33, v0
	v_mov_b32_e32 v34, v0
	v_mov_b32_e32 v35, v0
	v_mov_b32_e32 v36, v0
	v_mov_b32_e32 v37, v0
	v_mov_b32_e32 v38, v0
	v_mov_b32_e32 v39, v0
	v_mov_b32_e32 v120, v0
	v_mov_b32_e32 v121, v0
	v_mov_b32_e32 v122, v0
	v_mov_b32_e32 v123, v0
	v_mov_b32_e32 v124, v0
	v_mov_b32_e32 v125, v0
	v_mov_b32_e32 v126, v0
	v_mov_b32_e32 v127, v0
	v_mov_b32_e32 v104, v0
	v_mov_b32_e32 v105, v0
	v_mov_b32_e32 v106, v0
	v_mov_b32_e32 v107, v0
	v_mov_b32_e32 v108, v0
	v_mov_b32_e32 v109, v0
	v_mov_b32_e32 v110, v0
	v_mov_b32_e32 v111, v0
	v_mov_b32_e32 v84, v0
	v_mov_b32_e32 v85, v0
	v_mov_b32_e32 v86, v0
	v_mov_b32_e32 v87, v0
	v_mov_b32_e32 v88, v0
	v_mov_b32_e32 v89, v0
	v_mov_b32_e32 v90, v0
	v_mov_b32_e32 v91, v0
	v_mov_b32_e32 v56, v0
	v_mov_b32_e32 v57, v0
	v_mov_b32_e32 v58, v0
	v_mov_b32_e32 v59, v0
	v_mov_b32_e32 v60, v0
	v_mov_b32_e32 v61, v0
	v_mov_b32_e32 v62, v0
	v_mov_b32_e32 v63, v0
	s_andn2_b64 vcc, exec, s[0:1]
	s_cbranch_vccnz .LBB0_978
